# group barrier (workgroups with equal blockIdx%8, per-WG release/acquire) replaces the grid barrier at the P1-P2, P7-P8 and P8-P9 seams
# baseline (speedup 1.0000x reference)
; __device__ __forceinline__ unsigned xb_ld(unsigned* p)              { return __hip_atomic_load(p, __ATOMIC_RELAXED, __HIP_MEMORY_SCOPE_AGENT); }
; __device__ __forceinline__ unsigned xb_add(unsigned* p, unsigned v) { return __hip_atomic_fetch_add(p, v, __ATOMIC_RELAXED, __HIP_MEMORY_SCOPE_AGENT); }
; #define XB_SPIN(cond, bar) do { unsigned _sp = 0; while (cond) { __builtin_amdgcn_s_sleep(1); \
;     if ((++_sp & 255u) == 0u) { if (xb_ld(&(bar)[XB_TMO])) break; if (_sp > XB_SPIN_CAP) { atomicAdd(&(bar)[XB_TMO], 1u); break; } } } } while (0)
; #define SEAM(k) do { if (IN(k) && IN((k) + 1)) xcd_barrier(xbar); } while (0)
; __device__ __forceinline__ void xcd_barrier(const XcdBarrier& b) {
;     asm volatile("s_waitcnt vmcnt(0)" ::: "memory");
;     __syncthreads();
;     if (threadIdx.x == 0) {
;         unsigned* bar = b.bar;
;         __builtin_amdgcn_s_waitcnt(0);
;         unsigned nloc = b.st[0], nx = b.st[1];
;         if (nloc == 0u) { xcd_barrier_complete(bar, b.x, nloc, nx); b.st[0] = nloc; b.st[1] = nx; }
;         const unsigned old = xb_add(&bar[XB_XSUB(b.x)], 1u);
;         const unsigned gen = old / nloc;
;         if (old + 1u == (gen + 1u) * nloc) {
;             __builtin_amdgcn_fence(__ATOMIC_RELEASE, "agent");
;             asm volatile("s_waitcnt vmcnt(0)" ::: "memory");
;             const unsigned og = xb_add(&bar[XB_TOP], 1u);
;             const unsigned tg = og / nx;
;             if (og + 1u == (tg + 1u) * nx) xb_add(&bar[XB_TOPGEN], 1u);
;             else XB_SPIN(xb_ld(&bar[XB_TOPGEN]) == tg, bar);
;             __builtin_amdgcn_fence(__ATOMIC_ACQUIRE, "agent");
;             xb_add(&bar[XB_XGEN(b.x)], 1u);
;             asm volatile("s_waitcnt vmcnt(0)" ::: "memory");
;         } else {
;             XB_SPIN(xb_ld(&bar[XB_XGEN(b.x)]) == gen, bar);
;             __builtin_amdgcn_fence(__ATOMIC_ACQUIRE, "agent");
;             asm volatile("s_waitcnt vmcnt(0)" ::: "memory");
;         }
;     }
;     __syncthreads();
; }
; __global__ void __launch_bounds__(512, 2) fwd_megakernel(Args a) {
;     ...
;     SEAM(1);
.LBB0_211:
	s_cmp_gt_i32 s67, 2
	s_cselect_b64 s[2:3], -1, 0
	s_and_b64 s[0:1], s[6:7], s[2:3]
	s_andn2_b64 vcc, exec, s[0:1]
	s_cbranch_vccnz .LBB0_261
	s_waitcnt vmcnt(0)
	v_cmp_eq_u32_e32 vcc, 0, v220
	s_waitcnt lgkmcnt(0)
	s_barrier
	s_and_saveexec_b64 s[4:5], vcc
	s_cbranch_execz .LBB0_260
	buffer_wbl2 sc1
	s_waitcnt vmcnt(0) lgkmcnt(0)
	s_and_b32 s100, s77, 7
	s_lshl_b32 s101, s100, 6
	s_add_u32 s98, s64, s101
	s_addc_u32 s99, s65, 0
	s_add_u32 s98, s98, 0x83600
	s_addc_u32 s99, s99, 0
	s_sub_i32 s100, s82, s100
	s_add_i32 s100, s100, 7
	s_lshr_b32 s100, s100, 3
	s_add_i32 s100, s100, -1
	v_mov_b32_e32 v0, 0
	v_mov_b32_e32 v1, 1
	global_atomic_add v2, v0, v1, s[98:99] sc0
	s_waitcnt vmcnt(0)
	v_cmp_eq_u32_e32 vcc, s100, v2
	s_cbranch_vccnz .Lgb_release_1
.Lgb_spin_1:
	s_sleep 1
	global_load_dword v3, v0, s[98:99] offset:4 sc1
	s_waitcnt vmcnt(0)
	v_cmp_eq_u32_e32 vcc, 0, v3
	s_cbranch_vccnz .Lgb_spin_1
	s_branch .Lgb_done_1
.Lgb_release_1:
	global_atomic_add v0, v1, s[98:99] offset:4
.Lgb_done_1:
	buffer_inv sc1
	s_waitcnt vmcnt(0)

; __device__ __forceinline__ unsigned cvtpk(float lo, float hi) { f32x2_t v = {lo, hi}; bf16x2_t b = __builtin_convertvector(v, bf16x2_t); return __builtin_bit_cast(unsigned, b); }
;     __device__ __forceinline__ void operator()(const pg8::f32x4 (&acc)[2][2][4][2], const pg8::Unit& u, int wr, int wc, int fr, int fq) const {
;     ...
;         for (int ai = 0; ai < 2; ++ai)
; #pragma unroll
;             for (int m = 0; m < 4; ++m) {
;                 const int row = row0 + ai * 128 + m * 16;
;                 const float rs = rsqrtf(rsv[ai][m] * (1.f / DM) + EPS);
; #pragma unroll
;                 for (int bj = 0; bj < 2; ++bj) {
;                     pg8::f32x4 v0 = acc[ai][bj][m][0], v1 = acc[ai][bj][m][1];
;                     if (actm == 0) { v0 = v0 * rs; v1 = v1 * rs; }
;                     else {
;                         const float c1 = -rs * LOG2E, sc = (actm == 2) ? rs : 0.f;
; #pragma unroll
;                         for (int i = 0; i < 4; ++i) {
;                             const float s0 = __builtin_amdgcn_rcpf(1.f + __builtin_amdgcn_exp2f(v0[i] * c1)), s1 = __builtin_amdgcn_rcpf(1.f + __builtin_amdgcn_exp2f(v1[i] * c1));
;                             v0[i] = (actm == 2) ? v0[i] * sc * s0 : s0; v1[i] = (actm == 2) ? v1[i] * sc * s1 : s1; }
;                     }
;                     u32x4 w; w[0] = cvtpk(v0[0], v0[1]); w[1] = cvtpk(v0[2], v0[3]); w[2] = cvtpk(v1[0], v1[1]); w[3] = cvtpk(v1[2], v1[3]);
;                     *(u32x4*)(base + (size_t)row * ld + colt + bj * 128) = w;
;                 }
.LBB0_385:
	s_lshl_b32 s27, s27, 8
	s_and_b32 s10, s27, s10
	v_or_b32_e32 v144, s10, v172
	v_lshlrev_b32_e32 v144, 1, v144
	v_lshl_add_u64 v[158:159], s[6:7], 0, v[144:145]
	v_mad_i64_i32 v[168:169], s[6:7], s42, v156, 0
	v_lshl_add_u64 v[168:169], v[168:169], 1, v[158:159]
	v_cvt_pk_bf16_f32 v128, v128, v129
	v_cvt_pk_bf16_f32 v129, v130, v131
	v_cvt_pk_bf16_f32 v130, v132, v133
	v_cvt_pk_bf16_f32 v131, v134, v135
	s_xor_b64 s[44:45], s[44:45], -1
	global_store_dwordx4 v[168:169], v[128:131], off
	s_andn2_b64 vcc, exec, s[44:45]
	s_nop 0
	v_cndmask_b32_e64 v128, 0, 1, s[44:45]
	v_cmp_ne_u32_e64 s[6:7], 1, v128
	s_mov_b64 s[44:45], -1
	s_cbranch_vccnz .LBB0_387
	v_mul_f32_e32 v128, v116, v181
	v_exp_f32_e32 v128, v128
	v_mul_f32_e32 v129, v112, v181
	v_exp_f32_e32 v129, v129
	v_mul_f32_e32 v130, v116, v180
	v_add_f32_e32 v128, 1.0, v128
	v_rcp_f32_e32 v128, v128
	v_add_f32_e32 v129, 1.0, v129
	v_rcp_f32_e32 v129, v129
	v_mul_f32_e32 v131, v112, v180
	v_mul_f32_e32 v130, v130, v128
	v_cndmask_b32_e64 v128, v128, v130, s[4:5]
	v_mul_f32_e32 v130, v131, v129
	v_mul_f32_e32 v131, v117, v181
	v_exp_f32_e32 v131, v131
	v_mul_f32_e32 v132, v113, v181
	v_exp_f32_e32 v133, v132
	v_cndmask_b32_e64 v132, v129, v130, s[4:5]
	v_add_f32_e32 v129, 1.0, v131
	v_rcp_f32_e32 v129, v129
	v_add_f32_e32 v130, 1.0, v133
	v_rcp_f32_e32 v130, v130
	v_mul_f32_e32 v133, v118, v181
	v_mul_f32_e32 v131, v117, v180
	v_exp_f32_e32 v134, v133
	v_mul_f32_e32 v131, v131, v129
	v_mul_f32_e32 v133, v114, v181
	v_cndmask_b32_e64 v129, v129, v131, s[4:5]
	v_mul_f32_e32 v131, v113, v180
	v_exp_f32_e32 v135, v133
	v_mul_f32_e32 v131, v131, v130
	v_cndmask_b32_e64 v133, v130, v131, s[4:5]
	v_add_f32_e32 v130, 1.0, v134
	v_rcp_f32_e32 v130, v130
	v_add_f32_e32 v131, 1.0, v135
	v_rcp_f32_e32 v131, v131
	v_mul_f32_e32 v135, v119, v181
	v_mul_f32_e32 v134, v118, v180
	v_exp_f32_e32 v135, v135
	v_mul_f32_e32 v134, v134, v130
	v_mul_f32_e32 v144, v115, v181
	v_cndmask_b32_e64 v130, v130, v134, s[4:5]
	v_mul_f32_e32 v134, v114, v180
	v_exp_f32_e32 v144, v144
	v_mul_f32_e32 v134, v134, v131
	v_cndmask_b32_e64 v134, v131, v134, s[4:5]
	v_add_f32_e32 v131, 1.0, v135
	v_rcp_f32_e32 v131, v131
	v_add_f32_e32 v135, 1.0, v144
	v_rcp_f32_e32 v135, v135
	v_mul_f32_e32 v144, v119, v180
	v_mul_f32_e32 v144, v144, v131
	v_cndmask_b32_e64 v131, v131, v144, s[4:5]
	v_mul_f32_e32 v144, v115, v180
	v_mul_f32_e32 v144, v144, v135
	v_cndmask_b32_e64 v135, v135, v144, s[4:5]
	s_mov_b64 s[44:45], 0

; __device__ __forceinline__ unsigned cvtpk(float lo, float hi) { f32x2_t v = {lo, hi}; bf16x2_t b = __builtin_convertvector(v, bf16x2_t); return __builtin_bit_cast(unsigned, b); }
;     __device__ __forceinline__ void operator()(const pg8::f32x4 (&acc)[2][2][4][2], const pg8::Unit& u, int wr, int wc, int fr, int fq) const {
;     ...
;         for (int ai = 0; ai < 2; ++ai)
; #pragma unroll
;             for (int m = 0; m < 4; ++m) {
;                 const int row = row0 + ai * 128 + m * 16;
;                 const float rs = rsqrtf(rsv[ai][m] * (1.f / DM) + EPS);
; #pragma unroll
;                 for (int bj = 0; bj < 2; ++bj) {
;                     pg8::f32x4 v0 = acc[ai][bj][m][0], v1 = acc[ai][bj][m][1];
;                     if (actm == 0) { v0 = v0 * rs; v1 = v1 * rs; }
;                     else {
;                         const float c1 = -rs * LOG2E, sc = (actm == 2) ? rs : 0.f;
; #pragma unroll
;                         for (int i = 0; i < 4; ++i) {
;                             const float s0 = __builtin_amdgcn_rcpf(1.f + __builtin_amdgcn_exp2f(v0[i] * c1)), s1 = __builtin_amdgcn_rcpf(1.f + __builtin_amdgcn_exp2f(v1[i] * c1));
;                             v0[i] = (actm == 2) ? v0[i] * sc * s0 : s0; v1[i] = (actm == 2) ? v1[i] * sc * s1 : s1; }
;                     }
;                     u32x4 w; w[0] = cvtpk(v0[0], v0[1]); w[1] = cvtpk(v0[2], v0[3]); w[2] = cvtpk(v1[0], v1[1]); w[3] = cvtpk(v1[2], v1[3]);
;                     *(u32x4*)(base + (size_t)row * ld + colt + bj * 128) = w;
;                 }
.LBB0_389:
	v_cvt_pk_bf16_f32 v128, v128, v129
	v_cvt_pk_bf16_f32 v129, v130, v131
	v_fmamk_f32 v130, v165, 0x3a000000, v176
	v_mul_f32_e32 v131, 0x4b800000, v130
	v_cmp_gt_f32_e32 vcc, s55, v130
	s_mov_b64 s[44:45], -1
	s_nop 0
	v_cndmask_b32_e32 v130, v130, v131, vcc
	v_rsq_f32_e32 v144, v130
	v_cvt_pk_bf16_f32 v130, v132, v133
	v_cvt_pk_bf16_f32 v131, v134, v135
	global_store_dwordx4 v[168:169], v[128:131], off offset:256
	s_nop 1
	v_mul_f32_e32 v128, 0x45800000, v144
	v_cndmask_b32_e32 v166, v144, v128, vcc
	v_mul_f32_e32 v168, 0xbfb8aa3b, v166
	v_cndmask_b32_e64 v144, 0, v166, s[4:5]
	s_and_b64 vcc, exec, s[6:7]
	s_cbranch_vccnz .LBB0_391
	v_mul_f32_e32 v128, v108, v168
	v_exp_f32_e32 v128, v128
	v_mul_f32_e32 v129, v104, v168
	v_exp_f32_e32 v129, v129
	v_mul_f32_e32 v130, v108, v144
	v_add_f32_e32 v128, 1.0, v128
	v_rcp_f32_e32 v128, v128
	v_add_f32_e32 v129, 1.0, v129
	v_rcp_f32_e32 v129, v129
	v_mul_f32_e32 v131, v104, v144
	v_mul_f32_e32 v130, v130, v128
	v_cndmask_b32_e64 v128, v128, v130, s[4:5]
	v_mul_f32_e32 v130, v131, v129
	v_mul_f32_e32 v131, v109, v168
	v_exp_f32_e32 v131, v131
	v_mul_f32_e32 v132, v105, v168
	v_exp_f32_e32 v133, v132
	v_cndmask_b32_e64 v132, v129, v130, s[4:5]
	v_add_f32_e32 v129, 1.0, v131
	v_rcp_f32_e32 v129, v129
	v_add_f32_e32 v130, 1.0, v133
	v_rcp_f32_e32 v130, v130
	v_mul_f32_e32 v133, v110, v168
	v_mul_f32_e32 v131, v109, v144
	v_exp_f32_e32 v134, v133
	v_mul_f32_e32 v131, v131, v129
	v_mul_f32_e32 v133, v106, v168
	v_cndmask_b32_e64 v129, v129, v131, s[4:5]
	v_mul_f32_e32 v131, v105, v144
	v_exp_f32_e32 v135, v133
	v_mul_f32_e32 v131, v131, v130
	v_cndmask_b32_e64 v133, v130, v131, s[4:5]
	v_add_f32_e32 v130, 1.0, v134
	v_rcp_f32_e32 v130, v130
	v_add_f32_e32 v131, 1.0, v135
	v_rcp_f32_e32 v131, v131
	v_mul_f32_e32 v135, v111, v168
	v_mul_f32_e32 v134, v110, v144
	v_exp_f32_e32 v135, v135
	v_mul_f32_e32 v134, v134, v130
	v_mul_f32_e32 v165, v107, v168
	v_cndmask_b32_e64 v130, v130, v134, s[4:5]
	v_mul_f32_e32 v134, v106, v144
	v_exp_f32_e32 v165, v165
	v_mul_f32_e32 v134, v134, v131
	v_cndmask_b32_e64 v134, v131, v134, s[4:5]
	v_add_f32_e32 v131, 1.0, v135
	v_rcp_f32_e32 v131, v131
	v_add_f32_e32 v135, 1.0, v165
	v_rcp_f32_e32 v135, v135
	v_mul_f32_e32 v165, v111, v144
	v_mul_f32_e32 v165, v165, v131
	v_cndmask_b32_e64 v131, v131, v165, s[4:5]
	v_mul_f32_e32 v165, v107, v144
	v_mul_f32_e32 v165, v165, v135
	v_cndmask_b32_e64 v135, v135, v165, s[4:5]
	s_mov_b64 s[44:45], 0

; __device__ __forceinline__ unsigned cvtpk(float lo, float hi) { f32x2_t v = {lo, hi}; bf16x2_t b = __builtin_convertvector(v, bf16x2_t); return __builtin_bit_cast(unsigned, b); }
;     __device__ __forceinline__ void operator()(const pg8::f32x4 (&acc)[2][2][4][2], const pg8::Unit& u, int wr, int wc, int fr, int fq) const {
;     ...
;         for (int ai = 0; ai < 2; ++ai)
; #pragma unroll
;             for (int m = 0; m < 4; ++m) {
;                 const int row = row0 + ai * 128 + m * 16;
;                 const float rs = rsqrtf(rsv[ai][m] * (1.f / DM) + EPS);
; #pragma unroll
;                 for (int bj = 0; bj < 2; ++bj) {
;                     pg8::f32x4 v0 = acc[ai][bj][m][0], v1 = acc[ai][bj][m][1];
;                     if (actm == 0) { v0 = v0 * rs; v1 = v1 * rs; }
;                     else {
;                         const float c1 = -rs * LOG2E, sc = (actm == 2) ? rs : 0.f;
; #pragma unroll
;                         for (int i = 0; i < 4; ++i) {
;                             const float s0 = __builtin_amdgcn_rcpf(1.f + __builtin_amdgcn_exp2f(v0[i] * c1)), s1 = __builtin_amdgcn_rcpf(1.f + __builtin_amdgcn_exp2f(v1[i] * c1));
;                             v0[i] = (actm == 2) ? v0[i] * sc * s0 : s0; v1[i] = (actm == 2) ? v1[i] * sc * s1 : s1; }
;                     }
;                     u32x4 w; w[0] = cvtpk(v0[0], v0[1]); w[1] = cvtpk(v0[2], v0[3]); w[2] = cvtpk(v1[0], v1[1]); w[3] = cvtpk(v1[2], v1[3]);
;                     *(u32x4*)(base + (size_t)row * ld + colt + bj * 128) = w;
;                 }
.LBB0_393:
	v_mad_i64_i32 v[164:165], s[44:45], s42, v164, 0
	v_lshl_add_u64 v[164:165], v[164:165], 1, v[158:159]
	v_cvt_pk_bf16_f32 v128, v128, v129
	v_cvt_pk_bf16_f32 v129, v130, v131
	v_cvt_pk_bf16_f32 v130, v132, v133
	v_cvt_pk_bf16_f32 v131, v134, v135
	s_and_b64 vcc, exec, s[6:7]
	s_mov_b64 s[44:45], -1
	global_store_dwordx4 v[164:165], v[128:131], off
	s_cbranch_vccnz .LBB0_395
	s_nop 0
	v_mul_f32_e32 v128, v100, v168
	v_exp_f32_e32 v128, v128
	v_mul_f32_e32 v129, v96, v168
	v_exp_f32_e32 v129, v129
	v_mul_f32_e32 v130, v100, v144
	v_add_f32_e32 v128, 1.0, v128
	v_rcp_f32_e32 v128, v128
	v_add_f32_e32 v129, 1.0, v129
	v_rcp_f32_e32 v129, v129
	v_mul_f32_e32 v131, v96, v144
	v_mul_f32_e32 v130, v130, v128
	v_cndmask_b32_e64 v128, v128, v130, s[4:5]
	v_mul_f32_e32 v130, v131, v129
	v_mul_f32_e32 v131, v101, v168
	v_exp_f32_e32 v131, v131
	v_mul_f32_e32 v132, v97, v168
	v_exp_f32_e32 v133, v132
	v_cndmask_b32_e64 v132, v129, v130, s[4:5]
	v_add_f32_e32 v129, 1.0, v131
	v_rcp_f32_e32 v129, v129
	v_add_f32_e32 v130, 1.0, v133
	v_rcp_f32_e32 v130, v130
	v_mul_f32_e32 v133, v102, v168
	v_mul_f32_e32 v131, v101, v144
	v_exp_f32_e32 v134, v133
	v_mul_f32_e32 v131, v131, v129
	v_mul_f32_e32 v133, v98, v168
	v_cndmask_b32_e64 v129, v129, v131, s[4:5]
	v_mul_f32_e32 v131, v97, v144
	v_exp_f32_e32 v135, v133
	v_mul_f32_e32 v131, v131, v130
	v_cndmask_b32_e64 v133, v130, v131, s[4:5]
	v_add_f32_e32 v130, 1.0, v134
	v_rcp_f32_e32 v130, v130
	v_add_f32_e32 v131, 1.0, v135
	v_rcp_f32_e32 v131, v131
	v_mul_f32_e32 v135, v103, v168
	v_mul_f32_e32 v168, v99, v168
	v_mul_f32_e32 v134, v102, v144
	v_exp_f32_e32 v135, v135
	v_exp_f32_e32 v168, v168
	v_mul_f32_e32 v134, v134, v130
	v_cndmask_b32_e64 v130, v130, v134, s[4:5]
	v_mul_f32_e32 v134, v98, v144
	v_mul_f32_e32 v134, v134, v131
	v_cndmask_b32_e64 v134, v131, v134, s[4:5]
	v_add_f32_e32 v131, 1.0, v135
	v_add_f32_e32 v135, 1.0, v168
	v_rcp_f32_e32 v131, v131
	v_rcp_f32_e32 v135, v135
	v_mul_f32_e32 v168, v103, v144
	v_mul_f32_e32 v144, v99, v144
	v_mul_f32_e32 v168, v168, v131
	v_mul_f32_e32 v144, v144, v135
	v_cndmask_b32_e64 v131, v131, v168, s[4:5]
	v_cndmask_b32_e64 v135, v135, v144, s[4:5]
	s_mov_b64 s[44:45], 0

; __device__ __forceinline__ unsigned cvtpk(float lo, float hi) { f32x2_t v = {lo, hi}; bf16x2_t b = __builtin_convertvector(v, bf16x2_t); return __builtin_bit_cast(unsigned, b); }
;     __device__ __forceinline__ void operator()(const pg8::f32x4 (&acc)[2][2][4][2], const pg8::Unit& u, int wr, int wc, int fr, int fq) const {
;     ...
;         for (int ai = 0; ai < 2; ++ai)
; #pragma unroll
;             for (int m = 0; m < 4; ++m) {
;                 const int row = row0 + ai * 128 + m * 16;
;                 const float rs = rsqrtf(rsv[ai][m] * (1.f / DM) + EPS);
; #pragma unroll
;                 for (int bj = 0; bj < 2; ++bj) {
;                     pg8::f32x4 v0 = acc[ai][bj][m][0], v1 = acc[ai][bj][m][1];
;                     if (actm == 0) { v0 = v0 * rs; v1 = v1 * rs; }
;                     else {
;                         const float c1 = -rs * LOG2E, sc = (actm == 2) ? rs : 0.f;
; #pragma unroll
;                         for (int i = 0; i < 4; ++i) {
;                             const float s0 = __builtin_amdgcn_rcpf(1.f + __builtin_amdgcn_exp2f(v0[i] * c1)), s1 = __builtin_amdgcn_rcpf(1.f + __builtin_amdgcn_exp2f(v1[i] * c1));
;                             v0[i] = (actm == 2) ? v0[i] * sc * s0 : s0; v1[i] = (actm == 2) ? v1[i] * sc * s1 : s1; }
;                     }
;                     u32x4 w; w[0] = cvtpk(v0[0], v0[1]); w[1] = cvtpk(v0[2], v0[3]); w[2] = cvtpk(v1[0], v1[1]); w[3] = cvtpk(v1[2], v1[3]);
;                     *(u32x4*)(base + (size_t)row * ld + colt + bj * 128) = w;
;                 }
.LBB0_397:
	v_cvt_pk_bf16_f32 v128, v128, v129
	v_cvt_pk_bf16_f32 v129, v130, v131
	v_fmamk_f32 v130, v163, 0x3a000000, v176
	v_mul_f32_e32 v131, 0x4b800000, v130
	v_cmp_gt_f32_e32 vcc, s55, v130
	s_mov_b64 s[44:45], -1
	s_nop 0
	v_cndmask_b32_e32 v130, v130, v131, vcc
	v_rsq_f32_e32 v144, v130
	v_cvt_pk_bf16_f32 v130, v132, v133
	v_cvt_pk_bf16_f32 v131, v134, v135
	global_store_dwordx4 v[164:165], v[128:131], off offset:256
	s_nop 1
	v_mul_f32_e32 v128, 0x45800000, v144
	v_cndmask_b32_e32 v164, v144, v128, vcc
	v_mul_f32_e32 v166, 0xbfb8aa3b, v164
	v_cndmask_b32_e64 v144, 0, v164, s[4:5]
	s_and_b64 vcc, exec, s[6:7]
	s_cbranch_vccnz .LBB0_399
	v_mul_f32_e32 v128, v92, v166
	v_exp_f32_e32 v128, v128
	v_mul_f32_e32 v129, v88, v166
	v_exp_f32_e32 v129, v129
	v_mul_f32_e32 v130, v92, v144
	v_add_f32_e32 v128, 1.0, v128
	v_rcp_f32_e32 v128, v128
	v_add_f32_e32 v129, 1.0, v129
	v_rcp_f32_e32 v129, v129
	v_mul_f32_e32 v131, v88, v144
	v_mul_f32_e32 v130, v130, v128
	v_cndmask_b32_e64 v128, v128, v130, s[4:5]
	v_mul_f32_e32 v130, v131, v129
	v_mul_f32_e32 v131, v93, v166
	v_exp_f32_e32 v131, v131
	v_mul_f32_e32 v132, v89, v166
	v_exp_f32_e32 v133, v132
	v_cndmask_b32_e64 v132, v129, v130, s[4:5]
	v_add_f32_e32 v129, 1.0, v131
	v_rcp_f32_e32 v129, v129
	v_add_f32_e32 v130, 1.0, v133
	v_rcp_f32_e32 v130, v130
	v_mul_f32_e32 v133, v94, v166
	v_mul_f32_e32 v131, v93, v144
	v_exp_f32_e32 v134, v133
	v_mul_f32_e32 v131, v131, v129
	v_mul_f32_e32 v133, v90, v166
	v_cndmask_b32_e64 v129, v129, v131, s[4:5]
	v_mul_f32_e32 v131, v89, v144
	v_exp_f32_e32 v135, v133
	v_mul_f32_e32 v131, v131, v130
	v_cndmask_b32_e64 v133, v130, v131, s[4:5]
	v_add_f32_e32 v130, 1.0, v134
	v_rcp_f32_e32 v130, v130
	v_add_f32_e32 v131, 1.0, v135
	v_rcp_f32_e32 v131, v131
	v_mul_f32_e32 v135, v95, v166
	v_mul_f32_e32 v134, v94, v144
	v_exp_f32_e32 v135, v135
	v_mul_f32_e32 v134, v134, v130
	v_mul_f32_e32 v163, v91, v166
	v_cndmask_b32_e64 v130, v130, v134, s[4:5]
	v_mul_f32_e32 v134, v90, v144
	v_exp_f32_e32 v163, v163
	v_mul_f32_e32 v134, v134, v131
	v_cndmask_b32_e64 v134, v131, v134, s[4:5]
	v_add_f32_e32 v131, 1.0, v135
	v_rcp_f32_e32 v131, v131
	v_add_f32_e32 v135, 1.0, v163
	v_rcp_f32_e32 v135, v135
	v_mul_f32_e32 v163, v95, v144
	v_mul_f32_e32 v163, v163, v131
	v_cndmask_b32_e64 v131, v131, v163, s[4:5]
	v_mul_f32_e32 v163, v91, v144
	v_mul_f32_e32 v163, v163, v135
	v_cndmask_b32_e64 v135, v135, v163, s[4:5]
	s_mov_b64 s[44:45], 0

; __device__ __forceinline__ unsigned cvtpk(float lo, float hi) { f32x2_t v = {lo, hi}; bf16x2_t b = __builtin_convertvector(v, bf16x2_t); return __builtin_bit_cast(unsigned, b); }
;     __device__ __forceinline__ void operator()(const pg8::f32x4 (&acc)[2][2][4][2], const pg8::Unit& u, int wr, int wc, int fr, int fq) const {
;     ...
;         for (int ai = 0; ai < 2; ++ai)
; #pragma unroll
;             for (int m = 0; m < 4; ++m) {
;                 const int row = row0 + ai * 128 + m * 16;
;                 const float rs = rsqrtf(rsv[ai][m] * (1.f / DM) + EPS);
; #pragma unroll
;                 for (int bj = 0; bj < 2; ++bj) {
;                     pg8::f32x4 v0 = acc[ai][bj][m][0], v1 = acc[ai][bj][m][1];
;                     if (actm == 0) { v0 = v0 * rs; v1 = v1 * rs; }
;                     else {
;                         const float c1 = -rs * LOG2E, sc = (actm == 2) ? rs : 0.f;
; #pragma unroll
;                         for (int i = 0; i < 4; ++i) {
;                             const float s0 = __builtin_amdgcn_rcpf(1.f + __builtin_amdgcn_exp2f(v0[i] * c1)), s1 = __builtin_amdgcn_rcpf(1.f + __builtin_amdgcn_exp2f(v1[i] * c1));
;                             v0[i] = (actm == 2) ? v0[i] * sc * s0 : s0; v1[i] = (actm == 2) ? v1[i] * sc * s1 : s1; }
;                     }
;                     u32x4 w; w[0] = cvtpk(v0[0], v0[1]); w[1] = cvtpk(v0[2], v0[3]); w[2] = cvtpk(v1[0], v1[1]); w[3] = cvtpk(v1[2], v1[3]);
;                     *(u32x4*)(base + (size_t)row * ld + colt + bj * 128) = w;
;                 }
.LBB0_401:
	v_mad_i64_i32 v[162:163], s[44:45], s42, v162, 0
	v_lshl_add_u64 v[162:163], v[162:163], 1, v[158:159]
	v_cvt_pk_bf16_f32 v128, v128, v129
	v_cvt_pk_bf16_f32 v129, v130, v131
	v_cvt_pk_bf16_f32 v130, v132, v133
	v_cvt_pk_bf16_f32 v131, v134, v135
	s_and_b64 vcc, exec, s[6:7]
	s_mov_b64 s[44:45], -1
	global_store_dwordx4 v[162:163], v[128:131], off
	s_cbranch_vccnz .LBB0_403
	s_nop 0
	v_mul_f32_e32 v128, v84, v166
	v_exp_f32_e32 v128, v128
	v_mul_f32_e32 v129, v80, v166
	v_exp_f32_e32 v129, v129
	v_mul_f32_e32 v130, v84, v144
	v_add_f32_e32 v128, 1.0, v128
	v_rcp_f32_e32 v128, v128
	v_add_f32_e32 v129, 1.0, v129
	v_rcp_f32_e32 v129, v129
	v_mul_f32_e32 v131, v80, v144
	v_mul_f32_e32 v130, v130, v128
	v_cndmask_b32_e64 v128, v128, v130, s[4:5]
	v_mul_f32_e32 v130, v131, v129
	v_mul_f32_e32 v131, v85, v166
	v_exp_f32_e32 v131, v131
	v_mul_f32_e32 v132, v81, v166
	v_exp_f32_e32 v133, v132
	v_cndmask_b32_e64 v132, v129, v130, s[4:5]
	v_add_f32_e32 v129, 1.0, v131
	v_rcp_f32_e32 v129, v129
	v_add_f32_e32 v130, 1.0, v133
	v_rcp_f32_e32 v130, v130
	v_mul_f32_e32 v133, v86, v166
	v_mul_f32_e32 v131, v85, v144
	v_exp_f32_e32 v134, v133
	v_mul_f32_e32 v131, v131, v129
	v_mul_f32_e32 v133, v82, v166
	v_cndmask_b32_e64 v129, v129, v131, s[4:5]
	v_mul_f32_e32 v131, v81, v144
	v_exp_f32_e32 v135, v133
	v_mul_f32_e32 v131, v131, v130
	v_cndmask_b32_e64 v133, v130, v131, s[4:5]
	v_add_f32_e32 v130, 1.0, v134
	v_rcp_f32_e32 v130, v130
	v_add_f32_e32 v131, 1.0, v135
	v_rcp_f32_e32 v131, v131
	v_mul_f32_e32 v135, v87, v166
	v_mul_f32_e32 v166, v83, v166
	v_mul_f32_e32 v134, v86, v144
	v_exp_f32_e32 v135, v135
	v_exp_f32_e32 v166, v166
	v_mul_f32_e32 v134, v134, v130
	v_cndmask_b32_e64 v130, v130, v134, s[4:5]
	v_mul_f32_e32 v134, v82, v144
	v_mul_f32_e32 v134, v134, v131
	v_cndmask_b32_e64 v134, v131, v134, s[4:5]
	v_add_f32_e32 v131, 1.0, v135
	v_add_f32_e32 v135, 1.0, v166
	v_rcp_f32_e32 v131, v131
	v_rcp_f32_e32 v135, v135
	v_mul_f32_e32 v166, v87, v144
	v_mul_f32_e32 v144, v83, v144
	v_mul_f32_e32 v166, v166, v131
	v_mul_f32_e32 v144, v144, v135
	v_cndmask_b32_e64 v131, v131, v166, s[4:5]
	v_cndmask_b32_e64 v135, v135, v144, s[4:5]
	s_mov_b64 s[44:45], 0

; __device__ __forceinline__ unsigned cvtpk(float lo, float hi) { f32x2_t v = {lo, hi}; bf16x2_t b = __builtin_convertvector(v, bf16x2_t); return __builtin_bit_cast(unsigned, b); }
;     __device__ __forceinline__ void operator()(const pg8::f32x4 (&acc)[2][2][4][2], const pg8::Unit& u, int wr, int wc, int fr, int fq) const {
;     ...
;         for (int ai = 0; ai < 2; ++ai)
; #pragma unroll
;             for (int m = 0; m < 4; ++m) {
;                 const int row = row0 + ai * 128 + m * 16;
;                 const float rs = rsqrtf(rsv[ai][m] * (1.f / DM) + EPS);
; #pragma unroll
;                 for (int bj = 0; bj < 2; ++bj) {
;                     pg8::f32x4 v0 = acc[ai][bj][m][0], v1 = acc[ai][bj][m][1];
;                     if (actm == 0) { v0 = v0 * rs; v1 = v1 * rs; }
;                     else {
;                         const float c1 = -rs * LOG2E, sc = (actm == 2) ? rs : 0.f;
; #pragma unroll
;                         for (int i = 0; i < 4; ++i) {
;                             const float s0 = __builtin_amdgcn_rcpf(1.f + __builtin_amdgcn_exp2f(v0[i] * c1)), s1 = __builtin_amdgcn_rcpf(1.f + __builtin_amdgcn_exp2f(v1[i] * c1));
;                             v0[i] = (actm == 2) ? v0[i] * sc * s0 : s0; v1[i] = (actm == 2) ? v1[i] * sc * s1 : s1; }
;                     }
;                     u32x4 w; w[0] = cvtpk(v0[0], v0[1]); w[1] = cvtpk(v0[2], v0[3]); w[2] = cvtpk(v1[0], v1[1]); w[3] = cvtpk(v1[2], v1[3]);
;                     *(u32x4*)(base + (size_t)row * ld + colt + bj * 128) = w;
;                 }
.LBB0_405:
	v_cvt_pk_bf16_f32 v128, v128, v129
	v_cvt_pk_bf16_f32 v129, v130, v131
	v_fmamk_f32 v130, v161, 0x3a000000, v176
	v_mul_f32_e32 v131, 0x4b800000, v130
	v_cmp_gt_f32_e32 vcc, s55, v130
	s_mov_b64 s[44:45], -1
	s_nop 0
	v_cndmask_b32_e32 v130, v130, v131, vcc
	v_rsq_f32_e32 v144, v130
	v_cvt_pk_bf16_f32 v130, v132, v133
	v_cvt_pk_bf16_f32 v131, v134, v135
	global_store_dwordx4 v[162:163], v[128:131], off offset:256
	s_nop 1
	v_mul_f32_e32 v128, 0x45800000, v144
	v_cndmask_b32_e32 v162, v144, v128, vcc
	v_mul_f32_e32 v164, 0xbfb8aa3b, v162
	v_cndmask_b32_e64 v144, 0, v162, s[4:5]
	s_and_b64 vcc, exec, s[6:7]
	s_cbranch_vccnz .LBB0_407
	v_mul_f32_e32 v128, v76, v164
	v_exp_f32_e32 v128, v128
	v_mul_f32_e32 v129, v72, v164
	v_exp_f32_e32 v129, v129
	v_mul_f32_e32 v130, v76, v144
	v_add_f32_e32 v128, 1.0, v128
	v_rcp_f32_e32 v128, v128
	v_add_f32_e32 v129, 1.0, v129
	v_rcp_f32_e32 v129, v129
	v_mul_f32_e32 v131, v72, v144
	v_mul_f32_e32 v130, v130, v128
	v_cndmask_b32_e64 v128, v128, v130, s[4:5]
	v_mul_f32_e32 v130, v131, v129
	v_mul_f32_e32 v131, v77, v164
	v_exp_f32_e32 v131, v131
	v_mul_f32_e32 v132, v73, v164
	v_exp_f32_e32 v133, v132
	v_cndmask_b32_e64 v132, v129, v130, s[4:5]
	v_add_f32_e32 v129, 1.0, v131
	v_rcp_f32_e32 v129, v129
	v_add_f32_e32 v130, 1.0, v133
	v_rcp_f32_e32 v130, v130
	v_mul_f32_e32 v133, v78, v164
	v_mul_f32_e32 v131, v77, v144
	v_exp_f32_e32 v134, v133
	v_mul_f32_e32 v131, v131, v129
	v_mul_f32_e32 v133, v74, v164
	v_cndmask_b32_e64 v129, v129, v131, s[4:5]
	v_mul_f32_e32 v131, v73, v144
	v_exp_f32_e32 v135, v133
	v_mul_f32_e32 v131, v131, v130
	v_cndmask_b32_e64 v133, v130, v131, s[4:5]
	v_add_f32_e32 v130, 1.0, v134
	v_rcp_f32_e32 v130, v130
	v_add_f32_e32 v131, 1.0, v135
	v_rcp_f32_e32 v131, v131
	v_mul_f32_e32 v135, v79, v164
	v_mul_f32_e32 v134, v78, v144
	v_exp_f32_e32 v135, v135
	v_mul_f32_e32 v134, v134, v130
	v_mul_f32_e32 v161, v75, v164
	v_cndmask_b32_e64 v130, v130, v134, s[4:5]
	v_mul_f32_e32 v134, v74, v144
	v_exp_f32_e32 v161, v161
	v_mul_f32_e32 v134, v134, v131
	v_cndmask_b32_e64 v134, v131, v134, s[4:5]
	v_add_f32_e32 v131, 1.0, v135
	v_rcp_f32_e32 v131, v131
	v_add_f32_e32 v135, 1.0, v161
	v_rcp_f32_e32 v135, v135
	v_mul_f32_e32 v161, v79, v144
	v_mul_f32_e32 v161, v161, v131
	v_cndmask_b32_e64 v131, v131, v161, s[4:5]
	v_mul_f32_e32 v161, v75, v144
	v_mul_f32_e32 v161, v161, v135
	v_cndmask_b32_e64 v135, v135, v161, s[4:5]
	s_mov_b64 s[44:45], 0

; __device__ __forceinline__ unsigned cvtpk(float lo, float hi) { f32x2_t v = {lo, hi}; bf16x2_t b = __builtin_convertvector(v, bf16x2_t); return __builtin_bit_cast(unsigned, b); }
;     __device__ __forceinline__ void operator()(const pg8::f32x4 (&acc)[2][2][4][2], const pg8::Unit& u, int wr, int wc, int fr, int fq) const {
;     ...
;         for (int ai = 0; ai < 2; ++ai)
; #pragma unroll
;             for (int m = 0; m < 4; ++m) {
;                 const int row = row0 + ai * 128 + m * 16;
;                 const float rs = rsqrtf(rsv[ai][m] * (1.f / DM) + EPS);
; #pragma unroll
;                 for (int bj = 0; bj < 2; ++bj) {
;                     pg8::f32x4 v0 = acc[ai][bj][m][0], v1 = acc[ai][bj][m][1];
;                     if (actm == 0) { v0 = v0 * rs; v1 = v1 * rs; }
;                     else {
;                         const float c1 = -rs * LOG2E, sc = (actm == 2) ? rs : 0.f;
; #pragma unroll
;                         for (int i = 0; i < 4; ++i) {
;                             const float s0 = __builtin_amdgcn_rcpf(1.f + __builtin_amdgcn_exp2f(v0[i] * c1)), s1 = __builtin_amdgcn_rcpf(1.f + __builtin_amdgcn_exp2f(v1[i] * c1));
;                             v0[i] = (actm == 2) ? v0[i] * sc * s0 : s0; v1[i] = (actm == 2) ? v1[i] * sc * s1 : s1; }
;                     }
;                     u32x4 w; w[0] = cvtpk(v0[0], v0[1]); w[1] = cvtpk(v0[2], v0[3]); w[2] = cvtpk(v1[0], v1[1]); w[3] = cvtpk(v1[2], v1[3]);
;                     *(u32x4*)(base + (size_t)row * ld + colt + bj * 128) = w;
;                 }
.LBB0_409:
	v_mad_i64_i32 v[160:161], s[44:45], s42, v160, 0
	v_lshl_add_u64 v[160:161], v[160:161], 1, v[158:159]
	v_cvt_pk_bf16_f32 v128, v128, v129
	v_cvt_pk_bf16_f32 v129, v130, v131
	v_cvt_pk_bf16_f32 v130, v132, v133
	v_cvt_pk_bf16_f32 v131, v134, v135
	s_and_b64 vcc, exec, s[6:7]
	s_mov_b64 s[44:45], -1
	global_store_dwordx4 v[160:161], v[128:131], off
	s_cbranch_vccnz .LBB0_411
	s_nop 0
	v_mul_f32_e32 v128, v68, v164
	v_exp_f32_e32 v128, v128
	v_mul_f32_e32 v129, v64, v164
	v_exp_f32_e32 v129, v129
	v_mul_f32_e32 v130, v68, v144
	v_add_f32_e32 v128, 1.0, v128
	v_rcp_f32_e32 v128, v128
	v_add_f32_e32 v129, 1.0, v129
	v_rcp_f32_e32 v129, v129
	v_mul_f32_e32 v131, v64, v144
	v_mul_f32_e32 v130, v130, v128
	v_cndmask_b32_e64 v128, v128, v130, s[4:5]
	v_mul_f32_e32 v130, v131, v129
	v_mul_f32_e32 v131, v69, v164
	v_exp_f32_e32 v131, v131
	v_mul_f32_e32 v132, v65, v164
	v_exp_f32_e32 v133, v132
	v_cndmask_b32_e64 v132, v129, v130, s[4:5]
	v_add_f32_e32 v129, 1.0, v131
	v_rcp_f32_e32 v129, v129
	v_add_f32_e32 v130, 1.0, v133
	v_rcp_f32_e32 v130, v130
	v_mul_f32_e32 v133, v70, v164
	v_mul_f32_e32 v131, v69, v144
	v_exp_f32_e32 v134, v133
	v_mul_f32_e32 v131, v131, v129
	v_mul_f32_e32 v133, v66, v164
	v_cndmask_b32_e64 v129, v129, v131, s[4:5]
	v_mul_f32_e32 v131, v65, v144
	v_exp_f32_e32 v135, v133
	v_mul_f32_e32 v131, v131, v130
	v_cndmask_b32_e64 v133, v130, v131, s[4:5]
	v_add_f32_e32 v130, 1.0, v134
	v_rcp_f32_e32 v130, v130
	v_add_f32_e32 v131, 1.0, v135
	v_rcp_f32_e32 v131, v131
	v_mul_f32_e32 v135, v71, v164
	v_mul_f32_e32 v164, v67, v164
	v_mul_f32_e32 v134, v70, v144
	v_exp_f32_e32 v135, v135
	v_exp_f32_e32 v164, v164
	v_mul_f32_e32 v134, v134, v130
	v_cndmask_b32_e64 v130, v130, v134, s[4:5]
	v_mul_f32_e32 v134, v66, v144
	v_mul_f32_e32 v134, v134, v131
	v_cndmask_b32_e64 v134, v131, v134, s[4:5]
	v_add_f32_e32 v131, 1.0, v135
	v_add_f32_e32 v135, 1.0, v164
	v_rcp_f32_e32 v131, v131
	v_rcp_f32_e32 v135, v135
	v_mul_f32_e32 v164, v71, v144
	v_mul_f32_e32 v144, v67, v144
	v_mul_f32_e32 v164, v164, v131
	v_mul_f32_e32 v144, v144, v135
	v_cndmask_b32_e64 v131, v131, v164, s[4:5]
	v_cndmask_b32_e64 v135, v135, v144, s[4:5]
	s_mov_b64 s[44:45], 0

; __device__ __forceinline__ unsigned cvtpk(float lo, float hi) { f32x2_t v = {lo, hi}; bf16x2_t b = __builtin_convertvector(v, bf16x2_t); return __builtin_bit_cast(unsigned, b); }
;     __device__ __forceinline__ void operator()(const pg8::f32x4 (&acc)[2][2][4][2], const pg8::Unit& u, int wr, int wc, int fr, int fq) const {
;     ...
;         for (int ai = 0; ai < 2; ++ai)
; #pragma unroll
;             for (int m = 0; m < 4; ++m) {
;                 const int row = row0 + ai * 128 + m * 16;
;                 const float rs = rsqrtf(rsv[ai][m] * (1.f / DM) + EPS);
; #pragma unroll
;                 for (int bj = 0; bj < 2; ++bj) {
;                     pg8::f32x4 v0 = acc[ai][bj][m][0], v1 = acc[ai][bj][m][1];
;                     if (actm == 0) { v0 = v0 * rs; v1 = v1 * rs; }
;                     else {
;                         const float c1 = -rs * LOG2E, sc = (actm == 2) ? rs : 0.f;
; #pragma unroll
;                         for (int i = 0; i < 4; ++i) {
;                             const float s0 = __builtin_amdgcn_rcpf(1.f + __builtin_amdgcn_exp2f(v0[i] * c1)), s1 = __builtin_amdgcn_rcpf(1.f + __builtin_amdgcn_exp2f(v1[i] * c1));
;                             v0[i] = (actm == 2) ? v0[i] * sc * s0 : s0; v1[i] = (actm == 2) ? v1[i] * sc * s1 : s1; }
;                     }
;                     u32x4 w; w[0] = cvtpk(v0[0], v0[1]); w[1] = cvtpk(v0[2], v0[3]); w[2] = cvtpk(v1[0], v1[1]); w[3] = cvtpk(v1[2], v1[3]);
;                     *(u32x4*)(base + (size_t)row * ld + colt + bj * 128) = w;
;                 }
.LBB0_413:
	v_cvt_pk_bf16_f32 v128, v128, v129
	v_cvt_pk_bf16_f32 v129, v130, v131
	v_fmamk_f32 v130, v179, 0x3a000000, v176
	v_mul_f32_e32 v131, 0x4b800000, v130
	v_cmp_gt_f32_e32 vcc, s55, v130
	s_mov_b64 s[44:45], -1
	s_nop 0
	v_cndmask_b32_e32 v130, v130, v131, vcc
	v_rsq_f32_e32 v144, v130
	v_cvt_pk_bf16_f32 v130, v132, v133
	v_cvt_pk_bf16_f32 v131, v134, v135
	global_store_dwordx4 v[160:161], v[128:131], off offset:256
	s_nop 1
	v_mul_f32_e32 v128, 0x45800000, v144
	v_cndmask_b32_e32 v160, v144, v128, vcc
	v_mul_f32_e32 v164, 0xbfb8aa3b, v160
	v_cndmask_b32_e64 v144, 0, v160, s[4:5]
	s_and_b64 vcc, exec, s[6:7]
	s_cbranch_vccnz .LBB0_415
	v_mul_f32_e32 v128, v60, v164
	v_exp_f32_e32 v128, v128
	v_mul_f32_e32 v129, v56, v164
	v_exp_f32_e32 v129, v129
	v_mul_f32_e32 v130, v60, v144
	v_add_f32_e32 v128, 1.0, v128
	v_rcp_f32_e32 v128, v128
	v_add_f32_e32 v129, 1.0, v129
	v_rcp_f32_e32 v129, v129
	v_mul_f32_e32 v131, v56, v144
	v_mul_f32_e32 v130, v130, v128
	v_cndmask_b32_e64 v128, v128, v130, s[4:5]
	v_mul_f32_e32 v130, v131, v129
	v_mul_f32_e32 v131, v61, v164
	v_exp_f32_e32 v131, v131
	v_mul_f32_e32 v132, v57, v164
	v_exp_f32_e32 v133, v132
	v_cndmask_b32_e64 v132, v129, v130, s[4:5]
	v_add_f32_e32 v129, 1.0, v131
	v_rcp_f32_e32 v129, v129
	v_add_f32_e32 v130, 1.0, v133
	v_rcp_f32_e32 v130, v130
	v_mul_f32_e32 v133, v62, v164
	v_mul_f32_e32 v131, v61, v144
	v_exp_f32_e32 v134, v133
	v_mul_f32_e32 v131, v131, v129
	v_mul_f32_e32 v133, v58, v164
	v_cndmask_b32_e64 v129, v129, v131, s[4:5]
	v_mul_f32_e32 v131, v57, v144
	v_exp_f32_e32 v135, v133
	v_mul_f32_e32 v131, v131, v130
	v_cndmask_b32_e64 v133, v130, v131, s[4:5]
	v_add_f32_e32 v130, 1.0, v134
	v_rcp_f32_e32 v130, v130
	v_add_f32_e32 v131, 1.0, v135
	v_rcp_f32_e32 v131, v131
	v_mul_f32_e32 v135, v63, v164
	v_mul_f32_e32 v134, v62, v144
	v_exp_f32_e32 v135, v135
	v_mul_f32_e32 v134, v134, v130
	v_mul_f32_e32 v161, v59, v164
	v_cndmask_b32_e64 v130, v130, v134, s[4:5]
	v_mul_f32_e32 v134, v58, v144
	v_exp_f32_e32 v161, v161
	v_mul_f32_e32 v134, v134, v131
	v_cndmask_b32_e64 v134, v131, v134, s[4:5]
	v_add_f32_e32 v131, 1.0, v135
	v_rcp_f32_e32 v131, v131
	v_add_f32_e32 v135, 1.0, v161
	v_rcp_f32_e32 v135, v135
	v_mul_f32_e32 v161, v63, v144
	v_mul_f32_e32 v161, v161, v131
	v_cndmask_b32_e64 v131, v131, v161, s[4:5]
	v_mul_f32_e32 v161, v59, v144
	v_mul_f32_e32 v161, v161, v135
	v_cndmask_b32_e64 v135, v135, v161, s[4:5]
	s_mov_b64 s[44:45], 0

; __device__ __forceinline__ unsigned cvtpk(float lo, float hi) { f32x2_t v = {lo, hi}; bf16x2_t b = __builtin_convertvector(v, bf16x2_t); return __builtin_bit_cast(unsigned, b); }
;     __device__ __forceinline__ void operator()(const pg8::f32x4 (&acc)[2][2][4][2], const pg8::Unit& u, int wr, int wc, int fr, int fq) const {
;     ...
;         for (int ai = 0; ai < 2; ++ai)
; #pragma unroll
;             for (int m = 0; m < 4; ++m) {
;                 const int row = row0 + ai * 128 + m * 16;
;                 const float rs = rsqrtf(rsv[ai][m] * (1.f / DM) + EPS);
; #pragma unroll
;                 for (int bj = 0; bj < 2; ++bj) {
;                     pg8::f32x4 v0 = acc[ai][bj][m][0], v1 = acc[ai][bj][m][1];
;                     if (actm == 0) { v0 = v0 * rs; v1 = v1 * rs; }
;                     else {
;                         const float c1 = -rs * LOG2E, sc = (actm == 2) ? rs : 0.f;
; #pragma unroll
;                         for (int i = 0; i < 4; ++i) {
;                             const float s0 = __builtin_amdgcn_rcpf(1.f + __builtin_amdgcn_exp2f(v0[i] * c1)), s1 = __builtin_amdgcn_rcpf(1.f + __builtin_amdgcn_exp2f(v1[i] * c1));
;                             v0[i] = (actm == 2) ? v0[i] * sc * s0 : s0; v1[i] = (actm == 2) ? v1[i] * sc * s1 : s1; }
;                     }
;                     u32x4 w; w[0] = cvtpk(v0[0], v0[1]); w[1] = cvtpk(v0[2], v0[3]); w[2] = cvtpk(v1[0], v1[1]); w[3] = cvtpk(v1[2], v1[3]);
;                     *(u32x4*)(base + (size_t)row * ld + colt + bj * 128) = w;
;                 }
.LBB0_417:
	v_add_u32_e32 v162, 0x80, v156
	v_mad_i64_i32 v[162:163], s[44:45], s42, v162, 0
	v_lshl_add_u64 v[162:163], v[162:163], 1, v[158:159]
	v_cvt_pk_bf16_f32 v128, v128, v129
	v_cvt_pk_bf16_f32 v129, v130, v131
	v_cvt_pk_bf16_f32 v130, v132, v133
	v_cvt_pk_bf16_f32 v131, v134, v135
	s_and_b64 vcc, exec, s[6:7]
	s_mov_b64 s[44:45], -1
	global_store_dwordx4 v[162:163], v[128:131], off
	s_cbranch_vccnz .LBB0_419
	s_nop 0
	v_mul_f32_e32 v128, v52, v164
	v_exp_f32_e32 v128, v128
	v_mul_f32_e32 v129, v48, v164
	v_exp_f32_e32 v129, v129
	v_mul_f32_e32 v130, v52, v144
	v_add_f32_e32 v128, 1.0, v128
	v_rcp_f32_e32 v128, v128
	v_add_f32_e32 v129, 1.0, v129
	v_rcp_f32_e32 v129, v129
	v_mul_f32_e32 v131, v48, v144
	v_mul_f32_e32 v130, v130, v128
	v_cndmask_b32_e64 v128, v128, v130, s[4:5]
	v_mul_f32_e32 v130, v131, v129
	v_mul_f32_e32 v131, v53, v164
	v_exp_f32_e32 v131, v131
	v_mul_f32_e32 v132, v49, v164
	v_exp_f32_e32 v133, v132
	v_cndmask_b32_e64 v132, v129, v130, s[4:5]
	v_add_f32_e32 v129, 1.0, v131
	v_rcp_f32_e32 v129, v129
	v_add_f32_e32 v130, 1.0, v133
	v_rcp_f32_e32 v130, v130
	v_mul_f32_e32 v133, v54, v164
	v_mul_f32_e32 v131, v53, v144
	v_exp_f32_e32 v134, v133
	v_mul_f32_e32 v131, v131, v129
	v_mul_f32_e32 v133, v50, v164
	v_cndmask_b32_e64 v129, v129, v131, s[4:5]
	v_mul_f32_e32 v131, v49, v144
	v_exp_f32_e32 v135, v133
	v_mul_f32_e32 v131, v131, v130
	v_cndmask_b32_e64 v133, v130, v131, s[4:5]
	v_add_f32_e32 v130, 1.0, v134
	v_rcp_f32_e32 v130, v130
	v_add_f32_e32 v131, 1.0, v135
	v_rcp_f32_e32 v131, v131
	v_mul_f32_e32 v135, v55, v164
	v_mul_f32_e32 v164, v51, v164
	v_mul_f32_e32 v134, v54, v144
	v_exp_f32_e32 v135, v135
	v_exp_f32_e32 v164, v164
	v_mul_f32_e32 v134, v134, v130
	v_cndmask_b32_e64 v130, v130, v134, s[4:5]
	v_mul_f32_e32 v134, v50, v144
	v_mul_f32_e32 v134, v134, v131
	v_cndmask_b32_e64 v134, v131, v134, s[4:5]
	v_add_f32_e32 v131, 1.0, v135
	v_add_f32_e32 v135, 1.0, v164
	v_rcp_f32_e32 v131, v131
	v_rcp_f32_e32 v135, v135
	v_mul_f32_e32 v164, v55, v144
	v_mul_f32_e32 v144, v51, v144
	v_mul_f32_e32 v164, v164, v131
	v_mul_f32_e32 v144, v144, v135
	v_cndmask_b32_e64 v131, v131, v164, s[4:5]
	v_cndmask_b32_e64 v135, v135, v144, s[4:5]
	s_mov_b64 s[44:45], 0

; __device__ __forceinline__ unsigned cvtpk(float lo, float hi) { f32x2_t v = {lo, hi}; bf16x2_t b = __builtin_convertvector(v, bf16x2_t); return __builtin_bit_cast(unsigned, b); }
;     __device__ __forceinline__ void operator()(const pg8::f32x4 (&acc)[2][2][4][2], const pg8::Unit& u, int wr, int wc, int fr, int fq) const {
;     ...
;         for (int ai = 0; ai < 2; ++ai)
; #pragma unroll
;             for (int m = 0; m < 4; ++m) {
;                 const int row = row0 + ai * 128 + m * 16;
;                 const float rs = rsqrtf(rsv[ai][m] * (1.f / DM) + EPS);
; #pragma unroll
;                 for (int bj = 0; bj < 2; ++bj) {
;                     pg8::f32x4 v0 = acc[ai][bj][m][0], v1 = acc[ai][bj][m][1];
;                     if (actm == 0) { v0 = v0 * rs; v1 = v1 * rs; }
;                     else {
;                         const float c1 = -rs * LOG2E, sc = (actm == 2) ? rs : 0.f;
; #pragma unroll
;                         for (int i = 0; i < 4; ++i) {
;                             const float s0 = __builtin_amdgcn_rcpf(1.f + __builtin_amdgcn_exp2f(v0[i] * c1)), s1 = __builtin_amdgcn_rcpf(1.f + __builtin_amdgcn_exp2f(v1[i] * c1));
;                             v0[i] = (actm == 2) ? v0[i] * sc * s0 : s0; v1[i] = (actm == 2) ? v1[i] * sc * s1 : s1; }
;                     }
;                     u32x4 w; w[0] = cvtpk(v0[0], v0[1]); w[1] = cvtpk(v0[2], v0[3]); w[2] = cvtpk(v1[0], v1[1]); w[3] = cvtpk(v1[2], v1[3]);
;                     *(u32x4*)(base + (size_t)row * ld + colt + bj * 128) = w;
;                 }
.LBB0_421:
	v_cvt_pk_bf16_f32 v128, v128, v129
	v_cvt_pk_bf16_f32 v129, v130, v131
	v_fmamk_f32 v130, v178, 0x3a000000, v176
	v_mul_f32_e32 v131, 0x4b800000, v130
	v_cmp_gt_f32_e32 vcc, s55, v130
	s_mov_b64 s[44:45], -1
	s_nop 0
	v_cndmask_b32_e32 v130, v130, v131, vcc
	v_rsq_f32_e32 v144, v130
	v_cvt_pk_bf16_f32 v130, v132, v133
	v_cvt_pk_bf16_f32 v131, v134, v135
	global_store_dwordx4 v[162:163], v[128:131], off offset:256
	s_nop 1
	v_mul_f32_e32 v128, 0x45800000, v144
	v_cndmask_b32_e32 v160, v144, v128, vcc
	v_mul_f32_e32 v164, 0xbfb8aa3b, v160
	v_cndmask_b32_e64 v144, 0, v160, s[4:5]
	s_and_b64 vcc, exec, s[6:7]
	s_cbranch_vccnz .LBB0_423
	v_mul_f32_e32 v128, v44, v164
	v_exp_f32_e32 v128, v128
	v_mul_f32_e32 v129, v40, v164
	v_exp_f32_e32 v129, v129
	v_mul_f32_e32 v130, v44, v144
	v_add_f32_e32 v128, 1.0, v128
	v_rcp_f32_e32 v128, v128
	v_add_f32_e32 v129, 1.0, v129
	v_rcp_f32_e32 v129, v129
	v_mul_f32_e32 v131, v40, v144
	v_mul_f32_e32 v130, v130, v128
	v_cndmask_b32_e64 v128, v128, v130, s[4:5]
	v_mul_f32_e32 v130, v131, v129
	v_mul_f32_e32 v131, v45, v164
	v_exp_f32_e32 v131, v131
	v_mul_f32_e32 v132, v41, v164
	v_exp_f32_e32 v133, v132
	v_cndmask_b32_e64 v132, v129, v130, s[4:5]
	v_add_f32_e32 v129, 1.0, v131
	v_rcp_f32_e32 v129, v129
	v_add_f32_e32 v130, 1.0, v133
	v_rcp_f32_e32 v130, v130
	v_mul_f32_e32 v133, v46, v164
	v_mul_f32_e32 v131, v45, v144
	v_exp_f32_e32 v134, v133
	v_mul_f32_e32 v131, v131, v129
	v_mul_f32_e32 v133, v42, v164
	v_cndmask_b32_e64 v129, v129, v131, s[4:5]
	v_mul_f32_e32 v131, v41, v144
	v_exp_f32_e32 v135, v133
	v_mul_f32_e32 v131, v131, v130
	v_cndmask_b32_e64 v133, v130, v131, s[4:5]
	v_add_f32_e32 v130, 1.0, v134
	v_rcp_f32_e32 v130, v130
	v_add_f32_e32 v131, 1.0, v135
	v_rcp_f32_e32 v131, v131
	v_mul_f32_e32 v135, v47, v164
	v_mul_f32_e32 v134, v46, v144
	v_exp_f32_e32 v135, v135
	v_mul_f32_e32 v134, v134, v130
	v_mul_f32_e32 v161, v43, v164
	v_cndmask_b32_e64 v130, v130, v134, s[4:5]
	v_mul_f32_e32 v134, v42, v144
	v_exp_f32_e32 v161, v161
	v_mul_f32_e32 v134, v134, v131
	v_cndmask_b32_e64 v134, v131, v134, s[4:5]
	v_add_f32_e32 v131, 1.0, v135
	v_rcp_f32_e32 v131, v131
	v_add_f32_e32 v135, 1.0, v161
	v_rcp_f32_e32 v135, v135
	v_mul_f32_e32 v161, v47, v144
	v_mul_f32_e32 v161, v161, v131
	v_cndmask_b32_e64 v131, v131, v161, s[4:5]
	v_mul_f32_e32 v161, v43, v144
	v_mul_f32_e32 v161, v161, v135
	v_cndmask_b32_e64 v135, v135, v161, s[4:5]
	s_mov_b64 s[44:45], 0

; __device__ __forceinline__ unsigned cvtpk(float lo, float hi) { f32x2_t v = {lo, hi}; bf16x2_t b = __builtin_convertvector(v, bf16x2_t); return __builtin_bit_cast(unsigned, b); }
;     __device__ __forceinline__ void operator()(const pg8::f32x4 (&acc)[2][2][4][2], const pg8::Unit& u, int wr, int wc, int fr, int fq) const {
;     ...
;         for (int ai = 0; ai < 2; ++ai)
; #pragma unroll
;             for (int m = 0; m < 4; ++m) {
;                 const int row = row0 + ai * 128 + m * 16;
;                 const float rs = rsqrtf(rsv[ai][m] * (1.f / DM) + EPS);
; #pragma unroll
;                 for (int bj = 0; bj < 2; ++bj) {
;                     pg8::f32x4 v0 = acc[ai][bj][m][0], v1 = acc[ai][bj][m][1];
;                     if (actm == 0) { v0 = v0 * rs; v1 = v1 * rs; }
;                     else {
;                         const float c1 = -rs * LOG2E, sc = (actm == 2) ? rs : 0.f;
; #pragma unroll
;                         for (int i = 0; i < 4; ++i) {
;                             const float s0 = __builtin_amdgcn_rcpf(1.f + __builtin_amdgcn_exp2f(v0[i] * c1)), s1 = __builtin_amdgcn_rcpf(1.f + __builtin_amdgcn_exp2f(v1[i] * c1));
;                             v0[i] = (actm == 2) ? v0[i] * sc * s0 : s0; v1[i] = (actm == 2) ? v1[i] * sc * s1 : s1; }
;                     }
;                     u32x4 w; w[0] = cvtpk(v0[0], v0[1]); w[1] = cvtpk(v0[2], v0[3]); w[2] = cvtpk(v1[0], v1[1]); w[3] = cvtpk(v1[2], v1[3]);
;                     *(u32x4*)(base + (size_t)row * ld + colt + bj * 128) = w;
;                 }
.LBB0_425:
	v_add_u32_e32 v162, 0x90, v156
	v_mad_i64_i32 v[162:163], s[44:45], s42, v162, 0
	v_lshl_add_u64 v[162:163], v[162:163], 1, v[158:159]
	v_cvt_pk_bf16_f32 v128, v128, v129
	v_cvt_pk_bf16_f32 v129, v130, v131
	v_cvt_pk_bf16_f32 v130, v132, v133
	v_cvt_pk_bf16_f32 v131, v134, v135
	s_and_b64 vcc, exec, s[6:7]
	s_mov_b64 s[44:45], -1
	global_store_dwordx4 v[162:163], v[128:131], off
	s_cbranch_vccnz .LBB0_427
	s_nop 0
	v_mul_f32_e32 v128, v36, v164
	v_exp_f32_e32 v128, v128
	v_mul_f32_e32 v129, v32, v164
	v_exp_f32_e32 v129, v129
	v_mul_f32_e32 v130, v36, v144
	v_add_f32_e32 v128, 1.0, v128
	v_rcp_f32_e32 v128, v128
	v_add_f32_e32 v129, 1.0, v129
	v_rcp_f32_e32 v129, v129
	v_mul_f32_e32 v131, v32, v144
	v_mul_f32_e32 v130, v130, v128
	v_cndmask_b32_e64 v128, v128, v130, s[4:5]
	v_mul_f32_e32 v130, v131, v129
	v_mul_f32_e32 v131, v37, v164
	v_exp_f32_e32 v131, v131
	v_mul_f32_e32 v132, v33, v164
	v_exp_f32_e32 v133, v132
	v_cndmask_b32_e64 v132, v129, v130, s[4:5]
	v_add_f32_e32 v129, 1.0, v131
	v_rcp_f32_e32 v129, v129
	v_add_f32_e32 v130, 1.0, v133
	v_rcp_f32_e32 v130, v130
	v_mul_f32_e32 v133, v38, v164
	v_mul_f32_e32 v131, v37, v144
	v_exp_f32_e32 v134, v133
	v_mul_f32_e32 v131, v131, v129
	v_mul_f32_e32 v133, v34, v164
	v_cndmask_b32_e64 v129, v129, v131, s[4:5]
	v_mul_f32_e32 v131, v33, v144
	v_exp_f32_e32 v135, v133
	v_mul_f32_e32 v131, v131, v130
	v_cndmask_b32_e64 v133, v130, v131, s[4:5]
	v_add_f32_e32 v130, 1.0, v134
	v_rcp_f32_e32 v130, v130
	v_add_f32_e32 v131, 1.0, v135
	v_rcp_f32_e32 v131, v131
	v_mul_f32_e32 v135, v39, v164
	v_mul_f32_e32 v164, v35, v164
	v_mul_f32_e32 v134, v38, v144
	v_exp_f32_e32 v135, v135
	v_exp_f32_e32 v164, v164
	v_mul_f32_e32 v134, v134, v130
	v_cndmask_b32_e64 v130, v130, v134, s[4:5]
	v_mul_f32_e32 v134, v34, v144
	v_mul_f32_e32 v134, v134, v131
	v_cndmask_b32_e64 v134, v131, v134, s[4:5]
	v_add_f32_e32 v131, 1.0, v135
	v_add_f32_e32 v135, 1.0, v164
	v_rcp_f32_e32 v131, v131
	v_rcp_f32_e32 v135, v135
	v_mul_f32_e32 v164, v39, v144
	v_mul_f32_e32 v144, v35, v144
	v_mul_f32_e32 v164, v164, v131
	v_mul_f32_e32 v144, v144, v135
	v_cndmask_b32_e64 v131, v131, v164, s[4:5]
	v_cndmask_b32_e64 v135, v135, v144, s[4:5]
	s_mov_b64 s[44:45], 0

; __device__ __forceinline__ unsigned cvtpk(float lo, float hi) { f32x2_t v = {lo, hi}; bf16x2_t b = __builtin_convertvector(v, bf16x2_t); return __builtin_bit_cast(unsigned, b); }
;     __device__ __forceinline__ void operator()(const pg8::f32x4 (&acc)[2][2][4][2], const pg8::Unit& u, int wr, int wc, int fr, int fq) const {
;     ...
;         for (int ai = 0; ai < 2; ++ai)
; #pragma unroll
;             for (int m = 0; m < 4; ++m) {
;                 const int row = row0 + ai * 128 + m * 16;
;                 const float rs = rsqrtf(rsv[ai][m] * (1.f / DM) + EPS);
; #pragma unroll
;                 for (int bj = 0; bj < 2; ++bj) {
;                     pg8::f32x4 v0 = acc[ai][bj][m][0], v1 = acc[ai][bj][m][1];
;                     if (actm == 0) { v0 = v0 * rs; v1 = v1 * rs; }
;                     else {
;                         const float c1 = -rs * LOG2E, sc = (actm == 2) ? rs : 0.f;
; #pragma unroll
;                         for (int i = 0; i < 4; ++i) {
;                             const float s0 = __builtin_amdgcn_rcpf(1.f + __builtin_amdgcn_exp2f(v0[i] * c1)), s1 = __builtin_amdgcn_rcpf(1.f + __builtin_amdgcn_exp2f(v1[i] * c1));
;                             v0[i] = (actm == 2) ? v0[i] * sc * s0 : s0; v1[i] = (actm == 2) ? v1[i] * sc * s1 : s1; }
;                     }
;                     u32x4 w; w[0] = cvtpk(v0[0], v0[1]); w[1] = cvtpk(v0[2], v0[3]); w[2] = cvtpk(v1[0], v1[1]); w[3] = cvtpk(v1[2], v1[3]);
;                     *(u32x4*)(base + (size_t)row * ld + colt + bj * 128) = w;
;                 }
.LBB0_429:
	v_cvt_pk_bf16_f32 v128, v128, v129
	v_cvt_pk_bf16_f32 v129, v130, v131
	v_fmamk_f32 v130, v157, 0x3a000000, v176
	v_mul_f32_e32 v131, 0x4b800000, v130
	v_cmp_gt_f32_e32 vcc, s55, v130
	s_mov_b64 s[44:45], -1
	s_nop 0
	v_cndmask_b32_e32 v130, v130, v131, vcc
	v_rsq_f32_e32 v144, v130
	v_cvt_pk_bf16_f32 v130, v132, v133
	v_cvt_pk_bf16_f32 v131, v134, v135
	global_store_dwordx4 v[162:163], v[128:131], off offset:256
	s_nop 1
	v_mul_f32_e32 v128, 0x45800000, v144
	v_cndmask_b32_e32 v160, v144, v128, vcc
	v_mul_f32_e32 v157, 0xbfb8aa3b, v160
	v_cndmask_b32_e64 v144, 0, v160, s[4:5]
	s_and_b64 vcc, exec, s[6:7]
	s_cbranch_vccnz .LBB0_431
	v_mul_f32_e32 v128, v28, v157
	v_exp_f32_e32 v128, v128
	v_mul_f32_e32 v129, v24, v157
	v_exp_f32_e32 v129, v129
	v_mul_f32_e32 v130, v28, v144
	v_add_f32_e32 v128, 1.0, v128
	v_rcp_f32_e32 v128, v128
	v_add_f32_e32 v129, 1.0, v129
	v_rcp_f32_e32 v129, v129
	v_mul_f32_e32 v131, v24, v144
	v_mul_f32_e32 v130, v130, v128
	v_cndmask_b32_e64 v128, v128, v130, s[4:5]
	v_mul_f32_e32 v130, v131, v129
	v_mul_f32_e32 v131, v29, v157
	v_exp_f32_e32 v131, v131
	v_mul_f32_e32 v132, v25, v157
	v_exp_f32_e32 v133, v132
	v_cndmask_b32_e64 v132, v129, v130, s[4:5]
	v_add_f32_e32 v129, 1.0, v131
	v_rcp_f32_e32 v129, v129
	v_add_f32_e32 v130, 1.0, v133
	v_rcp_f32_e32 v130, v130
	v_mul_f32_e32 v133, v30, v157
	v_mul_f32_e32 v131, v29, v144
	v_exp_f32_e32 v134, v133
	v_mul_f32_e32 v131, v131, v129
	v_mul_f32_e32 v133, v26, v157
	v_cndmask_b32_e64 v129, v129, v131, s[4:5]
	v_mul_f32_e32 v131, v25, v144
	v_exp_f32_e32 v135, v133
	v_mul_f32_e32 v131, v131, v130
	v_cndmask_b32_e64 v133, v130, v131, s[4:5]
	v_add_f32_e32 v130, 1.0, v134
	v_rcp_f32_e32 v130, v130
	v_add_f32_e32 v131, 1.0, v135
	v_rcp_f32_e32 v131, v131
	v_mul_f32_e32 v135, v31, v157
	v_mul_f32_e32 v134, v30, v144
	v_exp_f32_e32 v135, v135
	v_mul_f32_e32 v134, v134, v130
	v_mul_f32_e32 v161, v27, v157
	v_cndmask_b32_e64 v130, v130, v134, s[4:5]
	v_mul_f32_e32 v134, v26, v144
	v_exp_f32_e32 v161, v161
	v_mul_f32_e32 v134, v134, v131
	v_cndmask_b32_e64 v134, v131, v134, s[4:5]
	v_add_f32_e32 v131, 1.0, v135
	v_rcp_f32_e32 v131, v131
	v_add_f32_e32 v135, 1.0, v161
	v_rcp_f32_e32 v135, v135
	v_mul_f32_e32 v161, v31, v144
	v_mul_f32_e32 v161, v161, v131
	v_cndmask_b32_e64 v131, v131, v161, s[4:5]
	v_mul_f32_e32 v161, v27, v144
	v_mul_f32_e32 v161, v161, v135
	v_cndmask_b32_e64 v135, v135, v161, s[4:5]
	s_mov_b64 s[44:45], 0

; __device__ __forceinline__ unsigned cvtpk(float lo, float hi) { f32x2_t v = {lo, hi}; bf16x2_t b = __builtin_convertvector(v, bf16x2_t); return __builtin_bit_cast(unsigned, b); }
;     __device__ __forceinline__ void operator()(const pg8::f32x4 (&acc)[2][2][4][2], const pg8::Unit& u, int wr, int wc, int fr, int fq) const {
;     ...
;         for (int ai = 0; ai < 2; ++ai)
; #pragma unroll
;             for (int m = 0; m < 4; ++m) {
;                 const int row = row0 + ai * 128 + m * 16;
;                 const float rs = rsqrtf(rsv[ai][m] * (1.f / DM) + EPS);
; #pragma unroll
;                 for (int bj = 0; bj < 2; ++bj) {
;                     pg8::f32x4 v0 = acc[ai][bj][m][0], v1 = acc[ai][bj][m][1];
;                     if (actm == 0) { v0 = v0 * rs; v1 = v1 * rs; }
;                     else {
;                         const float c1 = -rs * LOG2E, sc = (actm == 2) ? rs : 0.f;
; #pragma unroll
;                         for (int i = 0; i < 4; ++i) {
;                             const float s0 = __builtin_amdgcn_rcpf(1.f + __builtin_amdgcn_exp2f(v0[i] * c1)), s1 = __builtin_amdgcn_rcpf(1.f + __builtin_amdgcn_exp2f(v1[i] * c1));
;                             v0[i] = (actm == 2) ? v0[i] * sc * s0 : s0; v1[i] = (actm == 2) ? v1[i] * sc * s1 : s1; }
;                     }
;                     u32x4 w; w[0] = cvtpk(v0[0], v0[1]); w[1] = cvtpk(v0[2], v0[3]); w[2] = cvtpk(v1[0], v1[1]); w[3] = cvtpk(v1[2], v1[3]);
;                     *(u32x4*)(base + (size_t)row * ld + colt + bj * 128) = w;
;                 }
.LBB0_433:
	v_add_u32_e32 v162, 0xa0, v156
	v_mad_i64_i32 v[162:163], s[44:45], s42, v162, 0
	v_lshl_add_u64 v[162:163], v[162:163], 1, v[158:159]
	v_cvt_pk_bf16_f32 v128, v128, v129
	v_cvt_pk_bf16_f32 v129, v130, v131
	v_cvt_pk_bf16_f32 v130, v132, v133
	v_cvt_pk_bf16_f32 v131, v134, v135
	s_and_b64 vcc, exec, s[6:7]
	s_mov_b64 s[44:45], -1
	global_store_dwordx4 v[162:163], v[128:131], off
	s_cbranch_vccnz .LBB0_435
	s_nop 0
	v_mul_f32_e32 v128, v20, v157
	v_exp_f32_e32 v128, v128
	v_mul_f32_e32 v129, v16, v157
	v_exp_f32_e32 v129, v129
	v_mul_f32_e32 v130, v20, v144
	v_add_f32_e32 v128, 1.0, v128
	v_rcp_f32_e32 v128, v128
	v_add_f32_e32 v129, 1.0, v129
	v_rcp_f32_e32 v129, v129
	v_mul_f32_e32 v131, v16, v144
	v_mul_f32_e32 v130, v130, v128
	v_cndmask_b32_e64 v128, v128, v130, s[4:5]
	v_mul_f32_e32 v130, v131, v129
	v_mul_f32_e32 v131, v21, v157
	v_exp_f32_e32 v131, v131
	v_mul_f32_e32 v132, v17, v157
	v_exp_f32_e32 v133, v132
	v_cndmask_b32_e64 v132, v129, v130, s[4:5]
	v_add_f32_e32 v129, 1.0, v131
	v_rcp_f32_e32 v129, v129
	v_add_f32_e32 v130, 1.0, v133
	v_rcp_f32_e32 v130, v130
	v_mul_f32_e32 v133, v22, v157
	v_mul_f32_e32 v131, v21, v144
	v_exp_f32_e32 v134, v133
	v_mul_f32_e32 v131, v131, v129
	v_mul_f32_e32 v133, v18, v157
	v_cndmask_b32_e64 v129, v129, v131, s[4:5]
	v_mul_f32_e32 v131, v17, v144
	v_exp_f32_e32 v135, v133
	v_mul_f32_e32 v131, v131, v130
	v_cndmask_b32_e64 v133, v130, v131, s[4:5]
	v_add_f32_e32 v130, 1.0, v134
	v_rcp_f32_e32 v130, v130
	v_add_f32_e32 v131, 1.0, v135
	v_rcp_f32_e32 v131, v131
	v_mul_f32_e32 v135, v23, v157
	v_mul_f32_e32 v157, v19, v157
	v_mul_f32_e32 v134, v22, v144
	v_exp_f32_e32 v135, v135
	v_exp_f32_e32 v157, v157
	v_mul_f32_e32 v134, v134, v130
	v_cndmask_b32_e64 v130, v130, v134, s[4:5]
	v_mul_f32_e32 v134, v18, v144
	v_mul_f32_e32 v134, v134, v131
	v_cndmask_b32_e64 v134, v131, v134, s[4:5]
	v_add_f32_e32 v131, 1.0, v135
	v_add_f32_e32 v135, 1.0, v157
	v_rcp_f32_e32 v131, v131
	v_rcp_f32_e32 v135, v135
	v_mul_f32_e32 v157, v23, v144
	v_mul_f32_e32 v144, v19, v144
	v_mul_f32_e32 v157, v157, v131
	v_mul_f32_e32 v144, v144, v135
	v_cndmask_b32_e64 v131, v131, v157, s[4:5]
	v_cndmask_b32_e64 v135, v135, v144, s[4:5]
	s_mov_b64 s[44:45], 0

; __device__ __forceinline__ unsigned cvtpk(float lo, float hi) { f32x2_t v = {lo, hi}; bf16x2_t b = __builtin_convertvector(v, bf16x2_t); return __builtin_bit_cast(unsigned, b); }
;     __device__ __forceinline__ void operator()(const pg8::f32x4 (&acc)[2][2][4][2], const pg8::Unit& u, int wr, int wc, int fr, int fq) const {
;     ...
;         for (int ai = 0; ai < 2; ++ai)
; #pragma unroll
;             for (int m = 0; m < 4; ++m) {
;                 const int row = row0 + ai * 128 + m * 16;
;                 const float rs = rsqrtf(rsv[ai][m] * (1.f / DM) + EPS);
; #pragma unroll
;                 for (int bj = 0; bj < 2; ++bj) {
;                     pg8::f32x4 v0 = acc[ai][bj][m][0], v1 = acc[ai][bj][m][1];
;                     if (actm == 0) { v0 = v0 * rs; v1 = v1 * rs; }
;                     else {
;                         const float c1 = -rs * LOG2E, sc = (actm == 2) ? rs : 0.f;
; #pragma unroll
;                         for (int i = 0; i < 4; ++i) {
;                             const float s0 = __builtin_amdgcn_rcpf(1.f + __builtin_amdgcn_exp2f(v0[i] * c1)), s1 = __builtin_amdgcn_rcpf(1.f + __builtin_amdgcn_exp2f(v1[i] * c1));
;                             v0[i] = (actm == 2) ? v0[i] * sc * s0 : s0; v1[i] = (actm == 2) ? v1[i] * sc * s1 : s1; }
;                     }
;                     u32x4 w; w[0] = cvtpk(v0[0], v0[1]); w[1] = cvtpk(v0[2], v0[3]); w[2] = cvtpk(v1[0], v1[1]); w[3] = cvtpk(v1[2], v1[3]);
;                     *(u32x4*)(base + (size_t)row * ld + colt + bj * 128) = w;
;                 }
.LBB0_437:
	v_cvt_pk_bf16_f32 v128, v128, v129
	v_cvt_pk_bf16_f32 v129, v130, v131
	v_fmamk_f32 v130, v155, 0x3a000000, v176
	v_mul_f32_e32 v131, 0x4b800000, v130
	v_cmp_gt_f32_e32 vcc, s55, v130
	s_mov_b64 s[44:45], -1
	s_nop 0
	v_cndmask_b32_e32 v130, v130, v131, vcc
	v_rsq_f32_e32 v144, v130
	v_cvt_pk_bf16_f32 v130, v132, v133
	v_cvt_pk_bf16_f32 v131, v134, v135
	global_store_dwordx4 v[162:163], v[128:131], off offset:256
	s_nop 1
	v_mul_f32_e32 v128, 0x45800000, v144
	v_cndmask_b32_e32 v160, v144, v128, vcc
	v_mul_f32_e32 v155, 0xbfb8aa3b, v160
	v_cndmask_b32_e64 v144, 0, v160, s[4:5]
	s_and_b64 vcc, exec, s[6:7]
	s_cbranch_vccnz .LBB0_439
	v_mul_f32_e32 v128, v12, v155
	v_exp_f32_e32 v128, v128
	v_mul_f32_e32 v129, v8, v155
	v_exp_f32_e32 v129, v129
	v_mul_f32_e32 v130, v12, v144
	v_add_f32_e32 v128, 1.0, v128
	v_rcp_f32_e32 v128, v128
	v_add_f32_e32 v129, 1.0, v129
	v_rcp_f32_e32 v129, v129
	v_mul_f32_e32 v131, v8, v144
	v_mul_f32_e32 v130, v130, v128
	v_cndmask_b32_e64 v128, v128, v130, s[4:5]
	v_mul_f32_e32 v130, v131, v129
	v_mul_f32_e32 v131, v13, v155
	v_exp_f32_e32 v131, v131
	v_mul_f32_e32 v132, v9, v155
	v_exp_f32_e32 v133, v132
	v_cndmask_b32_e64 v132, v129, v130, s[4:5]
	v_add_f32_e32 v129, 1.0, v131
	v_rcp_f32_e32 v129, v129
	v_add_f32_e32 v130, 1.0, v133
	v_rcp_f32_e32 v130, v130
	v_mul_f32_e32 v133, v14, v155
	v_mul_f32_e32 v131, v13, v144
	v_exp_f32_e32 v134, v133
	v_mul_f32_e32 v131, v131, v129
	v_mul_f32_e32 v133, v10, v155
	v_cndmask_b32_e64 v129, v129, v131, s[4:5]
	v_mul_f32_e32 v131, v9, v144
	v_exp_f32_e32 v135, v133
	v_mul_f32_e32 v131, v131, v130
	v_cndmask_b32_e64 v133, v130, v131, s[4:5]
	v_add_f32_e32 v130, 1.0, v134
	v_rcp_f32_e32 v130, v130
	v_add_f32_e32 v131, 1.0, v135
	v_rcp_f32_e32 v131, v131
	v_mul_f32_e32 v135, v15, v155
	v_mul_f32_e32 v134, v14, v144
	v_exp_f32_e32 v135, v135
	v_mul_f32_e32 v134, v134, v130
	v_mul_f32_e32 v157, v11, v155
	v_cndmask_b32_e64 v130, v130, v134, s[4:5]
	v_mul_f32_e32 v134, v10, v144
	v_exp_f32_e32 v157, v157
	v_mul_f32_e32 v134, v134, v131
	v_cndmask_b32_e64 v134, v131, v134, s[4:5]
	v_add_f32_e32 v131, 1.0, v135
	v_rcp_f32_e32 v131, v131
	v_add_f32_e32 v135, 1.0, v157
	v_rcp_f32_e32 v135, v135
	v_mul_f32_e32 v157, v15, v144
	v_mul_f32_e32 v157, v157, v131
	v_cndmask_b32_e64 v131, v131, v157, s[4:5]
	v_mul_f32_e32 v157, v11, v144
	v_mul_f32_e32 v157, v157, v135
	v_cndmask_b32_e64 v135, v135, v157, s[4:5]
	s_mov_b64 s[44:45], 0

; __device__ __forceinline__ unsigned cvtpk(float lo, float hi) { f32x2_t v = {lo, hi}; bf16x2_t b = __builtin_convertvector(v, bf16x2_t); return __builtin_bit_cast(unsigned, b); }
;     __device__ __forceinline__ void operator()(const pg8::f32x4 (&acc)[2][2][4][2], const pg8::Unit& u, int wr, int wc, int fr, int fq) const {
;     ...
;         for (int ai = 0; ai < 2; ++ai)
; #pragma unroll
;             for (int m = 0; m < 4; ++m) {
;                 const int row = row0 + ai * 128 + m * 16;
;                 const float rs = rsqrtf(rsv[ai][m] * (1.f / DM) + EPS);
; #pragma unroll
;                 for (int bj = 0; bj < 2; ++bj) {
;                     pg8::f32x4 v0 = acc[ai][bj][m][0], v1 = acc[ai][bj][m][1];
;                     if (actm == 0) { v0 = v0 * rs; v1 = v1 * rs; }
;                     else {
;                         const float c1 = -rs * LOG2E, sc = (actm == 2) ? rs : 0.f;
; #pragma unroll
;                         for (int i = 0; i < 4; ++i) {
;                             const float s0 = __builtin_amdgcn_rcpf(1.f + __builtin_amdgcn_exp2f(v0[i] * c1)), s1 = __builtin_amdgcn_rcpf(1.f + __builtin_amdgcn_exp2f(v1[i] * c1));
;                             v0[i] = (actm == 2) ? v0[i] * sc * s0 : s0; v1[i] = (actm == 2) ? v1[i] * sc * s1 : s1; }
;                     }
;                     u32x4 w; w[0] = cvtpk(v0[0], v0[1]); w[1] = cvtpk(v0[2], v0[3]); w[2] = cvtpk(v1[0], v1[1]); w[3] = cvtpk(v1[2], v1[3]);
;                     *(u32x4*)(base + (size_t)row * ld + colt + bj * 128) = w;
;                 }
.LBB0_441:
	v_add_u32_e32 v156, 0xb0, v156
	v_mad_i64_i32 v[156:157], s[42:43], s42, v156, 0
	v_lshl_add_u64 v[156:157], v[156:157], 1, v[158:159]
	v_cvt_pk_bf16_f32 v128, v128, v129
	v_cvt_pk_bf16_f32 v129, v130, v131
	v_cvt_pk_bf16_f32 v130, v132, v133
	v_cvt_pk_bf16_f32 v131, v134, v135
	s_and_b64 vcc, exec, s[6:7]
	s_mov_b64 s[6:7], -1
	global_store_dwordx4 v[156:157], v[128:131], off
	s_cbranch_vccnz .LBB0_443
	s_nop 0
	v_mul_f32_e32 v128, v4, v155
	v_exp_f32_e32 v128, v128
	v_mul_f32_e32 v129, v0, v155
	v_exp_f32_e32 v129, v129
	v_mul_f32_e32 v130, v4, v144
	v_add_f32_e32 v128, 1.0, v128
	v_rcp_f32_e32 v128, v128
	v_add_f32_e32 v129, 1.0, v129
	v_rcp_f32_e32 v129, v129
	v_mul_f32_e32 v131, v0, v144
	v_mul_f32_e32 v130, v130, v128
	v_cndmask_b32_e64 v128, v128, v130, s[4:5]
	v_mul_f32_e32 v130, v131, v129
	v_mul_f32_e32 v131, v5, v155
	v_exp_f32_e32 v131, v131
	v_mul_f32_e32 v132, v1, v155
	v_exp_f32_e32 v133, v132
	v_cndmask_b32_e64 v132, v129, v130, s[4:5]
	v_add_f32_e32 v129, 1.0, v131
	v_rcp_f32_e32 v129, v129
	v_add_f32_e32 v130, 1.0, v133
	v_rcp_f32_e32 v130, v130
	v_mul_f32_e32 v133, v6, v155
	v_mul_f32_e32 v131, v5, v144
	v_exp_f32_e32 v134, v133
	v_mul_f32_e32 v131, v131, v129
	v_mul_f32_e32 v133, v2, v155
	v_cndmask_b32_e64 v129, v129, v131, s[4:5]
	v_mul_f32_e32 v131, v1, v144
	v_exp_f32_e32 v135, v133
	v_mul_f32_e32 v131, v131, v130
	v_cndmask_b32_e64 v133, v130, v131, s[4:5]
	v_add_f32_e32 v130, 1.0, v134
	v_rcp_f32_e32 v130, v130
	v_add_f32_e32 v131, 1.0, v135
	v_rcp_f32_e32 v131, v131
	v_mul_f32_e32 v135, v7, v155
	v_mul_f32_e32 v155, v3, v155
	v_mul_f32_e32 v134, v6, v144
	v_exp_f32_e32 v135, v135
	v_exp_f32_e32 v155, v155
	v_mul_f32_e32 v134, v134, v130
	v_cndmask_b32_e64 v130, v130, v134, s[4:5]
	v_mul_f32_e32 v134, v2, v144
	v_mul_f32_e32 v134, v134, v131
	v_cndmask_b32_e64 v134, v131, v134, s[4:5]
	v_add_f32_e32 v131, 1.0, v135
	v_add_f32_e32 v135, 1.0, v155
	v_rcp_f32_e32 v131, v131
	v_rcp_f32_e32 v135, v135
	v_mul_f32_e32 v155, v7, v144
	v_mul_f32_e32 v144, v3, v144
	v_mul_f32_e32 v155, v155, v131
	v_mul_f32_e32 v144, v144, v135
	v_cndmask_b32_e64 v131, v131, v155, s[4:5]
	v_cndmask_b32_e64 v135, v135, v144, s[4:5]
	s_mov_b64 s[6:7], 0

; __device__ __forceinline__ unsigned cvtpk(float lo, float hi) { f32x2_t v = {lo, hi}; bf16x2_t b = __builtin_convertvector(v, bf16x2_t); return __builtin_bit_cast(unsigned, b); }
;     __device__ __forceinline__ void operator()(const pg8::f32x4 (&acc)[2][2][4][2], const pg8::Unit& u, int wr, int wc, int fr, int fq) const {
;         if (u.pn < 8) {
;             bf16* qb_ = P + (size_t)(u.pn >> 2) * TOK * 1024 + (u.pn & 3) * 256 + 64 * wc + 8 * fq;
;             const int rowq = u.pm * 256 + wr * 64 + fr;
;             float rsq_[2][4];
; #pragma unroll
;             for (int ai = 0; ai < 2; ++ai)
; #pragma unroll
;                 for (int m = 0; m < 4; ++m) rsq_[ai][m] = ss[rowq + ai * 128 + m * 16];
; #pragma unroll
;             for (int ai = 0; ai < 2; ++ai)
; #pragma unroll
;                 for (int m = 0; m < 4; ++m) {
;                     const int row = rowq + ai * 128 + m * 16;
;                     const float rs = rsqrtf(rsq_[ai][m] * (1.f / DM) + EPS);
;                     const pg8::f32x4 a0 = acc[ai][0][m][0] * rs, a1 = acc[ai][0][m][1] * rs, b0 = acc[ai][1][m][0] * rs, b1 = acc[ai][1][m][1] * rs;
;                     float sq = (a0[0] * a0[0] + a0[1] * a0[1]) + (a0[2] * a0[2] + a0[3] * a0[3]) + (a1[0] * a1[0] + a1[1] * a1[1]) + (a1[2] * a1[2] + a1[3] * a1[3])
;                              + (b0[0] * b0[0] + b0[1] * b0[1]) + (b0[2] * b0[2] + b0[3] * b0[3]) + (b1[0] * b1[0] + b1[1] * b1[1]) + (b1[2] * b1[2] + b1[3] * b1[3]);
;                     sq += __shfl_xor(sq, 16); sq += __shfl_xor(sq, 32);
;                     const float rn = rsqrtf(sq * (1.f / 64.f) + EPS);
;     ...
;                     u32x4 w; w[0] = cvtpk(v0[0], v0[1]); w[1] = cvtpk(v0[2], v0[3]); w[2] = cvtpk(v1[0], v1[1]); w[3] = cvtpk(v1[2], v1[3]);
;                     *(u32x4*)(base + (size_t)row * ld + colt + bj * 128) = w;
.LBB0_445:
	v_cvt_pk_bf16_f32 v128, v128, v129
	v_cvt_pk_bf16_f32 v129, v130, v131
	v_cvt_pk_bf16_f32 v130, v132, v133
	v_cvt_pk_bf16_f32 v131, v134, v135
	global_store_dwordx4 v[156:157], v[128:131], off offset:256
	s_branch .LBB0_374
.LBB0_446:
	v_lshl_add_u32 v156, s40, 8, v170
	v_ashrrev_i32_e32 v157, 31, v156
	v_lshl_add_u64 v[132:133], v[156:157], 2, s[14:15]
	global_load_dword v163, v[132:133], off
	v_or_b32_e32 v134, 16, v156
	v_ashrrev_i32_e32 v135, 31, v134
	v_lshl_add_u64 v[128:129], v[134:135], 2, s[14:15]
	global_load_dword v168, v[128:129], off
	v_and_b32_e32 v129, 64, v177
	v_xor_b32_e32 v144, 16, v177
	v_add_u32_e32 v159, 64, v129
	v_xor_b32_e32 v158, 32, v177
	v_cmp_lt_i32_e32 vcc, v144, v159
	v_or_b32_e32 v130, 32, v156
	v_or_b32_e32 v128, 48, v156
	v_cndmask_b32_e32 v144, v177, v144, vcc
	v_cmp_lt_i32_e32 vcc, v158, v159
	v_ashrrev_i32_e32 v131, 31, v130
	v_ashrrev_i32_e32 v129, 31, v128
	v_cndmask_b32_e32 v159, v177, v158, vcc
	s_ashr_i32 s4, s36, 2
	v_lshl_add_u64 v[164:165], v[130:131], 2, s[14:15]
	v_lshl_add_u64 v[166:167], v[128:129], 2, s[14:15]
	v_lshlrev_b32_e32 v158, 2, v144
	v_lshlrev_b32_e32 v144, 2, v159
	global_load_dword v162, v[132:133], off offset:512
	global_load_dword v161, v[132:133], off offset:576
	global_load_dword v160, v[132:133], off offset:640
	global_load_dword v192, v[164:165], off
	global_load_dword v193, v[166:167], off
	global_load_dword v159, v[132:133], off offset:704
	s_ashr_i32 s5, s4, 31
	s_lshl_b64 s[4:5], s[4:5], 25
	s_add_u32 s4, s84, s4
	s_addc_u32 s5, s85, s5
	s_lshl_b32 s6, s36, 9
	s_and_b32 s6, s6, 0x600
	s_add_u32 s4, s4, s6
	s_addc_u32 s5, s5, 0
	s_add_u32 s6, s4, s56
	s_addc_u32 s7, s5, 0
	v_mov_b32_e32 v155, v145
	s_waitcnt vmcnt(0)
	v_fmamk_f32 v132, v163, 0x3a000000, v176
	v_mul_f32_e32 v133, 0x4b800000, v132
	v_cmp_gt_f32_e32 vcc, s55, v132
	v_fmamk_f32 v163, v168, 0x3a000000, v176
	s_nop 0
	v_cndmask_b32_e32 v132, v132, v133, vcc
	v_rsq_f32_e32 v164, v132
	v_mul_f32_e32 v133, 0x4b800000, v163
	v_cmp_gt_f32_e64 s[4:5], s55, v163
	s_nop 1
	v_cndmask_b32_e64 v132, v163, v133, s[4:5]
	v_rsq_f32_e32 v163, v132
	v_lshl_add_u64 v[132:133], s[6:7], 0, v[154:155]
	v_mul_f32_e32 v155, 0x45800000, v164
	v_cndmask_b32_e32 v164, v164, v155, vcc
	v_pk_mul_f32 v[124:125], v[124:125], v[164:165] op_sel_hi:[1,0]
	v_pk_mul_f32 v[126:127], v[126:127], v[164:165] op_sel_hi:[1,0]
	v_pk_mul_f32 v[120:121], v[120:121], v[164:165] op_sel_hi:[1,0]
	v_pk_mul_f32 v[122:123], v[122:123], v[164:165] op_sel_hi:[1,0]
	v_pk_mul_f32 v[166:167], v[126:127], v[126:127]
	v_pk_mul_f32 v[168:169], v[124:125], v[124:125]
	v_pk_mul_f32 v[178:179], v[122:123], v[122:123]
	v_pk_mul_f32 v[180:181], v[120:121], v[120:121]
	v_pk_mov_b32 v[190:191], v[168:169], v[166:167] op_sel:[1,0]
	v_mov_b32_e32 v169, v167
	v_mul_f32_e32 v155, 0x45800000, v163
	v_pk_mul_f32 v[116:117], v[116:117], v[164:165] op_sel_hi:[1,0]
	v_pk_mul_f32 v[118:119], v[118:119], v[164:165] op_sel_hi:[1,0]
	v_mov_b32_e32 v166, v178
	v_mov_b32_e32 v167, v180
	v_mov_b32_e32 v180, v179
	v_pk_add_f32 v[168:169], v[190:191], v[168:169]
	v_pk_mul_f32 v[112:113], v[112:113], v[164:165] op_sel_hi:[1,0]
	v_pk_mul_f32 v[114:115], v[114:115], v[164:165] op_sel_hi:[1,0]
	v_cndmask_b32_e64 v164, v163, v155, s[4:5]
	v_pk_mul_f32 v[182:183], v[118:119], v[118:119]
	v_pk_mul_f32 v[184:185], v[116:117], v[116:117]
	v_pk_add_f32 v[166:167], v[166:167], v[180:181]
	v_add_f32_e32 v155, v168, v169
	v_mov_b32_e32 v178, v182
	v_mov_b32_e32 v179, v184
	v_mov_b32_e32 v184, v183
	v_add_f32_e32 v155, v167, v155
	v_pk_mul_f32 v[186:187], v[114:115], v[114:115]
	v_pk_mul_f32 v[188:189], v[112:113], v[112:113]
	v_pk_add_f32 v[178:179], v[178:179], v[184:185]
	v_add_f32_e32 v155, v166, v155
	v_mov_b32_e32 v182, v186
	v_mov_b32_e32 v183, v188
	v_mov_b32_e32 v188, v187
	v_add_f32_e32 v155, v179, v155
	v_pk_add_f32 v[180:181], v[182:183], v[188:189]
	v_add_f32_e32 v155, v178, v155
	v_add_f32_e32 v155, v181, v155
	v_add_f32_e32 v155, v180, v155
	ds_bpermute_b32 v163, v158, v155
	v_pk_mul_f32 v[166:167], v[104:105], v[164:165] op_sel_hi:[1,0]
	v_pk_mul_f32 v[180:181], v[96:97], v[164:165] op_sel_hi:[1,0]
	v_pk_mul_f32 v[108:109], v[108:109], v[164:165] op_sel_hi:[1,0]
	v_pk_mul_f32 v[110:111], v[110:111], v[164:165] op_sel_hi:[1,0]
	s_waitcnt lgkmcnt(0)
	v_add_f32_e32 v104, v155, v163
	ds_bpermute_b32 v105, v144, v104
	v_pk_mul_f32 v[106:107], v[106:107], v[164:165] op_sel_hi:[1,0]
	v_pk_mul_f32 v[168:169], v[100:101], v[164:165] op_sel_hi:[1,0]
	v_pk_mul_f32 v[178:179], v[102:103], v[164:165] op_sel_hi:[1,0]
	v_pk_mul_f32 v[164:165], v[98:99], v[164:165] op_sel_hi:[1,0]
	s_waitcnt lgkmcnt(0)
; __device__ __forceinline__ unsigned cvtpk(float lo, float hi) { f32x2_t v = {lo, hi}; bf16x2_t b = __builtin_convertvector(v, bf16x2_t); return __builtin_bit_cast(unsigned, b); }
;     __device__ __forceinline__ void operator()(const pg8::f32x4 (&acc)[2][2][4][2], const pg8::Unit& u, int wr, int wc, int fr, int fq) const {
;     ...
;                 for (int m = 0; m < 4; ++m) {
;                     const int row = rowq + ai * 128 + m * 16;
;                     const float rs = rsqrtf(rsq_[ai][m] * (1.f / DM) + EPS);
;                     const pg8::f32x4 a0 = acc[ai][0][m][0] * rs, a1 = acc[ai][0][m][1] * rs, b0 = acc[ai][1][m][0] * rs, b1 = acc[ai][1][m][1] * rs;
;                     float sq = (a0[0] * a0[0] + a0[1] * a0[1]) + (a0[2] * a0[2] + a0[3] * a0[3]) + (a1[0] * a1[0] + a1[1] * a1[1]) + (a1[2] * a1[2] + a1[3] * a1[3])
;                              + (b0[0] * b0[0] + b0[1] * b0[1]) + (b0[2] * b0[2] + b0[3] * b0[3]) + (b1[0] * b1[0] + b1[1] * b1[1]) + (b1[2] * b1[2] + b1[3] * b1[3]);
;                     sq += __shfl_xor(sq, 16); sq += __shfl_xor(sq, 32);
;                     const float rn = rsqrtf(sq * (1.f / 64.f) + EPS);
;                     u32x4 w0, w1;
;                     w0[0] = cvtpk(a0[0] * rn, a0[1] * rn); w0[1] = cvtpk(a0[2] * rn, a0[3] * rn); w0[2] = cvtpk(a1[0] * rn, a1[1] * rn); w0[3] = cvtpk(a1[2] * rn, a1[3] * rn);
;                     w1[0] = cvtpk(b0[0] * rn, b0[1] * rn); w1[1] = cvtpk(b0[2] * rn, b0[3] * rn); w1[2] = cvtpk(b1[0] * rn, b1[1] * rn); w1[3] = cvtpk(b1[2] * rn, b1[3] * rn);
;                     *(u32x4*)(qb_ + (size_t)row * 1024) = w0; *(u32x4*)(qb_ + (size_t)row * 1024 + 32) = w1;
	v_add_f32_e32 v96, v104, v105
	v_fmamk_f32 v96, v96, 0x3c800000, v176
	v_mul_f32_e32 v97, 0x4b800000, v96
	v_cmp_gt_f32_e32 vcc, s55, v96
	v_pk_mul_f32 v[102:103], v[108:109], v[108:109]
	s_mov_b64 s[4:5], 0x40000
	v_cndmask_b32_e32 v96, v96, v97, vcc
	v_rsq_f32_e32 v98, v96
	v_pk_mul_f32 v[96:97], v[110:111], v[110:111]
	s_nop 0
	v_pk_mov_b32 v[104:105], v[102:103], v[96:97] op_sel:[1,0]
	v_mul_f32_e32 v96, 0x45800000, v98
	v_cndmask_b32_e32 v96, v98, v96, vcc
	v_pk_mul_f32 v[98:99], v[124:125], v[96:97] op_sel_hi:[1,0]
	v_pk_mul_f32 v[100:101], v[126:127], v[96:97] op_sel_hi:[1,0]
	v_pk_mul_f32 v[120:121], v[120:121], v[96:97] op_sel_hi:[1,0]
	v_mov_b32_e32 v103, v97
	v_pk_mul_f32 v[122:123], v[122:123], v[96:97] op_sel_hi:[1,0]
	v_cvt_pk_bf16_f32 v98, v98, v99
	v_cvt_pk_bf16_f32 v99, v100, v101
	v_cvt_pk_bf16_f32 v100, v120, v121
	v_pk_add_f32 v[102:103], v[104:105], v[102:103]
	v_pk_mul_f32 v[104:105], v[106:107], v[106:107]
	v_pk_mul_f32 v[120:121], v[166:167], v[166:167]
	v_cvt_pk_bf16_f32 v101, v122, v123
	v_mov_b32_e32 v122, v104
	v_mov_b32_e32 v123, v120
	v_mov_b32_e32 v120, v105
	v_pk_mul_f32 v[116:117], v[116:117], v[96:97] op_sel_hi:[1,0]
	v_pk_add_f32 v[104:105], v[122:123], v[120:121]
	v_pk_mul_f32 v[120:121], v[178:179], v[178:179]
	v_pk_mul_f32 v[122:123], v[168:169], v[168:169]
	v_add_f32_e32 v97, v102, v103
	v_mov_b32_e32 v124, v120
	v_mov_b32_e32 v125, v122
	v_mov_b32_e32 v122, v121
	v_add_f32_e32 v97, v105, v97
	v_pk_add_f32 v[120:121], v[124:125], v[122:123]
	v_pk_mul_f32 v[122:123], v[164:165], v[164:165]
	v_pk_mul_f32 v[124:125], v[180:181], v[180:181]
	v_add_f32_e32 v97, v104, v97
	v_mov_b32_e32 v126, v122
	v_mov_b32_e32 v127, v124
	v_mov_b32_e32 v124, v123
	v_add_f32_e32 v97, v121, v97
	v_pk_add_f32 v[122:123], v[126:127], v[124:125]
	v_add_f32_e32 v97, v120, v97
	v_add_f32_e32 v97, v123, v97
	v_add_f32_e32 v97, v122, v97
	ds_bpermute_b32 v120, v158, v97
	v_pk_mul_f32 v[104:105], v[118:119], v[96:97] op_sel_hi:[1,0]
	v_cvt_pk_bf16_f32 v102, v116, v117
	v_cvt_pk_bf16_f32 v103, v104, v105
	v_pk_mul_f32 v[104:105], v[112:113], v[96:97] op_sel_hi:[1,0]
	s_waitcnt lgkmcnt(0)
	v_add_f32_e32 v112, v97, v120
	ds_bpermute_b32 v113, v144, v112
	v_pk_mul_f32 v[96:97], v[114:115], v[96:97] op_sel_hi:[1,0]
	v_cvt_pk_bf16_f32 v104, v104, v105
	v_cvt_pk_bf16_f32 v105, v96, v97
	v_lshlrev_b64 v[96:97], 11, v[156:157]
	s_waitcnt lgkmcnt(0)
	v_add_f32_e32 v112, v112, v113
	v_fmamk_f32 v112, v112, 0x3c800000, v176
	v_mul_f32_e32 v113, 0x4b800000, v112
	v_cmp_gt_f32_e32 vcc, s55, v112
	v_lshl_add_u64 v[96:97], v[132:133], 0, v[96:97]
	global_store_dwordx4 v[96:97], v[98:101], off
	global_store_dwordx4 v[96:97], v[102:105], off offset:64
	v_cndmask_b32_e32 v112, v112, v113, vcc
	v_rsq_f32_e32 v112, v112
	s_nop 0
	v_mul_f32_e32 v98, 0x45800000, v112
	v_cndmask_b32_e32 v102, v112, v98, vcc
	v_pk_mul_f32 v[98:99], v[108:109], v[102:103] op_sel_hi:[1,0]
	v_pk_mul_f32 v[100:101], v[110:111], v[102:103] op_sel_hi:[1,0]
	v_cvt_pk_bf16_f32 v98, v98, v99
	v_cvt_pk_bf16_f32 v99, v100, v101
	v_pk_mul_f32 v[100:101], v[166:167], v[102:103] op_sel_hi:[1,0]
	s_nop 0
	v_cvt_pk_bf16_f32 v100, v100, v101
	v_fmamk_f32 v101, v192, 0x3a000000, v176
	v_mul_f32_e32 v103, 0x4b800000, v101
	v_cmp_gt_f32_e32 vcc, s55, v101
	s_nop 1
	v_cndmask_b32_e32 v101, v101, v103, vcc
	v_rsq_f32_e32 v103, v101
	s_nop 0
	v_pk_mul_f32 v[104:105], v[106:107], v[102:103] op_sel_hi:[1,0]
	v_mul_f32_e32 v106, 0x45800000, v103
	v_cndmask_b32_e32 v106, v103, v106, vcc
	v_pk_mul_f32 v[92:93], v[92:93], v[106:107] op_sel_hi:[1,0]
	v_pk_mul_f32 v[94:95], v[94:95], v[106:107] op_sel_hi:[1,0]
	v_pk_mul_f32 v[88:89], v[88:89], v[106:107] op_sel_hi:[1,0]
	v_pk_mul_f32 v[90:91], v[90:91], v[106:107] op_sel_hi:[1,0]
	v_pk_mul_f32 v[84:85], v[84:85], v[106:107] op_sel_hi:[1,0]
	v_pk_mul_f32 v[86:87], v[86:87], v[106:107] op_sel_hi:[1,0]
	v_pk_mul_f32 v[108:109], v[80:81], v[106:107] op_sel_hi:[1,0]
	v_pk_mul_f32 v[106:107], v[82:83], v[106:107] op_sel_hi:[1,0]
	v_pk_mul_f32 v[80:81], v[94:95], v[94:95]
	v_pk_mul_f32 v[82:83], v[92:93], v[92:93]
	v_cvt_pk_bf16_f32 v101, v104, v105
	v_pk_mov_b32 v[110:111], v[82:83], v[80:81] op_sel:[1,0]
	v_mov_b32_e32 v83, v81
	v_pk_add_f32 v[80:81], v[110:111], v[82:83]
	v_pk_mul_f32 v[82:83], v[90:91], v[90:91]
	v_pk_mul_f32 v[110:111], v[88:89], v[88:89]
	v_mov_b32_e32 v112, v82
	v_mov_b32_e32 v113, v110
	v_mov_b32_e32 v110, v83
	v_pk_add_f32 v[82:83], v[112:113], v[110:111]
	v_pk_mul_f32 v[110:111], v[86:87], v[86:87]
	v_pk_mul_f32 v[112:113], v[84:85], v[84:85]
	v_add_f32_e32 v80, v80, v81
	v_mov_b32_e32 v114, v110
	v_mov_b32_e32 v115, v112
	v_mov_b32_e32 v112, v111
	v_add_f32_e32 v80, v83, v80
	v_pk_add_f32 v[110:111], v[114:115], v[112:113]
	v_pk_mul_f32 v[112:113], v[106:107], v[106:107]
	v_pk_mul_f32 v[114:115], v[108:109], v[108:109]
	v_add_f32_e32 v80, v82, v80
	v_mov_b32_e32 v116, v112
	v_mov_b32_e32 v117, v114
	v_mov_b32_e32 v114, v113
	v_add_f32_e32 v80, v111, v80
	v_pk_add_f32 v[112:113], v[116:117], v[114:115]
	v_add_f32_e32 v80, v110, v80
	v_add_f32_e32 v80, v113, v80
	v_pk_mul_f32 v[104:105], v[168:169], v[102:103] op_sel_hi:[1,0]
	v_add_f32_e32 v103, v112, v80
	ds_bpermute_b32 v110, v158, v103
	v_cvt_pk_bf16_f32 v80, v104, v105
	v_pk_mul_f32 v[82:83], v[178:179], v[102:103] op_sel_hi:[1,0]
	s_waitcnt lgkmcnt(0)
	v_add_f32_e32 v104, v103, v110
	ds_bpermute_b32 v105, v144, v104
	v_cvt_pk_bf16_f32 v81, v82, v83
	v_pk_mul_f32 v[82:83], v[180:181], v[102:103] op_sel_hi:[1,0]
	v_pk_mul_f32 v[102:103], v[164:165], v[102:103] op_sel_hi:[1,0]
	v_cvt_pk_bf16_f32 v82, v82, v83
	s_waitcnt lgkmcnt(0)
; __device__ __forceinline__ unsigned cvtpk(float lo, float hi) { f32x2_t v = {lo, hi}; bf16x2_t b = __builtin_convertvector(v, bf16x2_t); return __builtin_bit_cast(unsigned, b); }
;     __device__ __forceinline__ void operator()(const pg8::f32x4 (&acc)[2][2][4][2], const pg8::Unit& u, int wr, int wc, int fr, int fq) const {
;     ...
;                 for (int m = 0; m < 4; ++m) {
;                     const int row = rowq + ai * 128 + m * 16;
;                     const float rs = rsqrtf(rsq_[ai][m] * (1.f / DM) + EPS);
;                     const pg8::f32x4 a0 = acc[ai][0][m][0] * rs, a1 = acc[ai][0][m][1] * rs, b0 = acc[ai][1][m][0] * rs, b1 = acc[ai][1][m][1] * rs;
;                     float sq = (a0[0] * a0[0] + a0[1] * a0[1]) + (a0[2] * a0[2] + a0[3] * a0[3]) + (a1[0] * a1[0] + a1[1] * a1[1]) + (a1[2] * a1[2] + a1[3] * a1[3])
;                              + (b0[0] * b0[0] + b0[1] * b0[1]) + (b0[2] * b0[2] + b0[3] * b0[3]) + (b1[0] * b1[0] + b1[1] * b1[1]) + (b1[2] * b1[2] + b1[3] * b1[3]);
;                     sq += __shfl_xor(sq, 16); sq += __shfl_xor(sq, 32);
;                     const float rn = rsqrtf(sq * (1.f / 64.f) + EPS);
;                     u32x4 w0, w1;
;                     w0[0] = cvtpk(a0[0] * rn, a0[1] * rn); w0[1] = cvtpk(a0[2] * rn, a0[3] * rn); w0[2] = cvtpk(a1[0] * rn, a1[1] * rn); w0[3] = cvtpk(a1[2] * rn, a1[3] * rn);
;                     w1[0] = cvtpk(b0[0] * rn, b0[1] * rn); w1[1] = cvtpk(b0[2] * rn, b0[3] * rn); w1[2] = cvtpk(b1[0] * rn, b1[1] * rn); w1[3] = cvtpk(b1[2] * rn, b1[3] * rn);
;                     *(u32x4*)(qb_ + (size_t)row * 1024) = w0; *(u32x4*)(qb_ + (size_t)row * 1024 + 32) = w1;
	v_add_f32_e32 v104, v104, v105
	v_fmamk_f32 v104, v104, 0x3c800000, v176
	v_mul_f32_e32 v105, 0x4b800000, v104
	v_cmp_gt_f32_e32 vcc, s55, v104
	v_cvt_pk_bf16_f32 v83, v102, v103
	v_lshlrev_b64 v[102:103], 11, v[134:135]
	v_cndmask_b32_e32 v104, v104, v105, vcc
	v_rsq_f32_e32 v104, v104
	v_lshl_add_u64 v[102:103], v[132:133], 0, v[102:103]
	global_store_dwordx4 v[102:103], v[98:101], off
	global_store_dwordx4 v[102:103], v[80:83], off offset:64
	s_nop 1
	v_mul_f32_e32 v80, 0x45800000, v104
	v_cndmask_b32_e32 v98, v104, v80, vcc
	v_pk_mul_f32 v[80:81], v[92:93], v[98:99] op_sel_hi:[1,0]
	v_pk_mul_f32 v[82:83], v[94:95], v[98:99] op_sel_hi:[1,0]
	v_cvt_pk_bf16_f32 v80, v80, v81
	v_cvt_pk_bf16_f32 v81, v82, v83
	v_pk_mul_f32 v[82:83], v[88:89], v[98:99] op_sel_hi:[1,0]
	v_pk_mul_f32 v[84:85], v[84:85], v[98:99] op_sel_hi:[1,0]
	v_cvt_pk_bf16_f32 v82, v82, v83
	v_fmamk_f32 v83, v193, 0x3a000000, v176
	v_mul_f32_e32 v88, 0x4b800000, v83
	v_cmp_gt_f32_e32 vcc, s55, v83
	s_nop 1
	v_cndmask_b32_e32 v83, v83, v88, vcc
	v_rsq_f32_e32 v92, v83
	v_pk_mul_f32 v[88:89], v[90:91], v[98:99] op_sel_hi:[1,0]
	s_nop 0
	v_cvt_pk_bf16_f32 v83, v88, v89
	v_mul_f32_e32 v88, 0x45800000, v92
	v_cndmask_b32_e32 v88, v92, v88, vcc
	v_pk_mul_f32 v[76:77], v[76:77], v[88:89] op_sel_hi:[1,0]
	v_pk_mul_f32 v[78:79], v[78:79], v[88:89] op_sel_hi:[1,0]
	v_pk_mul_f32 v[72:73], v[72:73], v[88:89] op_sel_hi:[1,0]
	v_pk_mul_f32 v[74:75], v[74:75], v[88:89] op_sel_hi:[1,0]
	v_pk_mul_f32 v[68:69], v[68:69], v[88:89] op_sel_hi:[1,0]
	v_pk_mul_f32 v[70:71], v[70:71], v[88:89] op_sel_hi:[1,0]
	v_pk_mul_f32 v[90:91], v[64:65], v[88:89] op_sel_hi:[1,0]
	v_pk_mul_f32 v[88:89], v[66:67], v[88:89] op_sel_hi:[1,0]
	v_pk_mul_f32 v[64:65], v[78:79], v[78:79]
	v_pk_mul_f32 v[66:67], v[76:77], v[76:77]
	s_nop 0
	v_pk_mov_b32 v[92:93], v[66:67], v[64:65] op_sel:[1,0]
	v_mov_b32_e32 v67, v65
	v_pk_add_f32 v[64:65], v[92:93], v[66:67]
	v_pk_mul_f32 v[66:67], v[74:75], v[74:75]
	v_pk_mul_f32 v[92:93], v[72:73], v[72:73]
	v_mov_b32_e32 v94, v66
	v_mov_b32_e32 v95, v92
	v_mov_b32_e32 v92, v67
	v_pk_add_f32 v[66:67], v[94:95], v[92:93]
	v_pk_mul_f32 v[92:93], v[70:71], v[70:71]
	v_pk_mul_f32 v[94:95], v[68:69], v[68:69]
	v_add_f32_e32 v64, v64, v65
	v_mov_b32_e32 v100, v92
	v_mov_b32_e32 v101, v94
	v_mov_b32_e32 v94, v93
	v_add_f32_e32 v64, v67, v64
	v_pk_add_f32 v[92:93], v[100:101], v[94:95]
	v_pk_mul_f32 v[94:95], v[88:89], v[88:89]
	v_pk_mul_f32 v[100:101], v[90:91], v[90:91]
	v_add_f32_e32 v64, v66, v64
	v_mov_b32_e32 v102, v94
	v_mov_b32_e32 v103, v100
	v_mov_b32_e32 v100, v95
	v_add_f32_e32 v64, v93, v64
	v_pk_add_f32 v[94:95], v[102:103], v[100:101]
	v_add_f32_e32 v64, v92, v64
	v_add_f32_e32 v64, v95, v64
	v_add_f32_e32 v92, v94, v64
	ds_bpermute_b32 v93, v158, v92
	v_pk_mul_f32 v[66:67], v[86:87], v[98:99] op_sel_hi:[1,0]
	v_cvt_pk_bf16_f32 v64, v84, v85
	v_cvt_pk_bf16_f32 v65, v66, v67
	v_pk_mul_f32 v[66:67], v[108:109], v[98:99] op_sel_hi:[1,0]
	s_waitcnt lgkmcnt(0)
	v_add_f32_e32 v86, v92, v93
	ds_bpermute_b32 v87, v144, v86
	v_pk_mul_f32 v[84:85], v[106:107], v[98:99] op_sel_hi:[1,0]
	v_cvt_pk_bf16_f32 v66, v66, v67
	v_cvt_pk_bf16_f32 v67, v84, v85
	v_lshlrev_b64 v[84:85], 11, v[130:131]
	s_waitcnt lgkmcnt(0)
	v_add_f32_e32 v86, v86, v87
	v_fmamk_f32 v86, v86, 0x3c800000, v176
	v_mul_f32_e32 v87, 0x4b800000, v86
	v_cmp_gt_f32_e32 vcc, s55, v86
	v_lshl_add_u64 v[84:85], v[132:133], 0, v[84:85]
	global_store_dwordx4 v[84:85], v[80:83], off
	global_store_dwordx4 v[84:85], v[64:67], off offset:64
	v_cndmask_b32_e32 v86, v86, v87, vcc
	v_rsq_f32_e32 v86, v86
	s_nop 0
	v_mul_f32_e32 v64, 0x45800000, v86
	v_cndmask_b32_e32 v80, v86, v64, vcc
	v_pk_mul_f32 v[64:65], v[76:77], v[80:81] op_sel_hi:[1,0]
	v_pk_mul_f32 v[66:67], v[78:79], v[80:81] op_sel_hi:[1,0]
	v_cvt_pk_bf16_f32 v64, v64, v65
	v_cvt_pk_bf16_f32 v65, v66, v67
	v_pk_mul_f32 v[66:67], v[72:73], v[80:81] op_sel_hi:[1,0]
	v_pk_mul_f32 v[68:69], v[68:69], v[80:81] op_sel_hi:[1,0]
	v_cvt_pk_bf16_f32 v66, v66, v67
	v_fmamk_f32 v67, v162, 0x3a000000, v176
	v_mul_f32_e32 v72, 0x4b800000, v67
	v_cmp_gt_f32_e32 vcc, s55, v67
	s_nop 1
	v_cndmask_b32_e32 v67, v67, v72, vcc
	v_rsq_f32_e32 v76, v67
	v_pk_mul_f32 v[72:73], v[74:75], v[80:81] op_sel_hi:[1,0]
	s_nop 0
	v_cvt_pk_bf16_f32 v67, v72, v73
	v_mul_f32_e32 v72, 0x45800000, v76
	v_cndmask_b32_e32 v72, v76, v72, vcc
	v_pk_mul_f32 v[60:61], v[60:61], v[72:73] op_sel_hi:[1,0]
	v_pk_mul_f32 v[62:63], v[62:63], v[72:73] op_sel_hi:[1,0]
	v_pk_mul_f32 v[56:57], v[56:57], v[72:73] op_sel_hi:[1,0]
	v_pk_mul_f32 v[58:59], v[58:59], v[72:73] op_sel_hi:[1,0]
	v_pk_mul_f32 v[52:53], v[52:53], v[72:73] op_sel_hi:[1,0]
	v_pk_mul_f32 v[54:55], v[54:55], v[72:73] op_sel_hi:[1,0]
	v_pk_mul_f32 v[74:75], v[48:49], v[72:73] op_sel_hi:[1,0]
	v_pk_mul_f32 v[72:73], v[50:51], v[72:73] op_sel_hi:[1,0]
	v_pk_mul_f32 v[48:49], v[62:63], v[62:63]
	v_pk_mul_f32 v[50:51], v[60:61], v[60:61]
	s_nop 0
	v_pk_mov_b32 v[76:77], v[50:51], v[48:49] op_sel:[1,0]
	v_mov_b32_e32 v51, v49
	v_pk_add_f32 v[48:49], v[76:77], v[50:51]
	v_pk_mul_f32 v[50:51], v[58:59], v[58:59]
	v_pk_mul_f32 v[76:77], v[56:57], v[56:57]
	v_mov_b32_e32 v78, v50
	v_mov_b32_e32 v79, v76
	v_mov_b32_e32 v76, v51
	v_pk_add_f32 v[50:51], v[78:79], v[76:77]
	v_pk_mul_f32 v[76:77], v[54:55], v[54:55]
	v_pk_mul_f32 v[78:79], v[52:53], v[52:53]
	v_add_f32_e32 v48, v48, v49
	v_mov_b32_e32 v82, v76
	v_mov_b32_e32 v83, v78
	v_mov_b32_e32 v78, v77
	v_add_f32_e32 v48, v51, v48
	v_pk_add_f32 v[76:77], v[82:83], v[78:79]
	v_pk_mul_f32 v[78:79], v[72:73], v[72:73]
	v_pk_mul_f32 v[82:83], v[74:75], v[74:75]
	v_add_f32_e32 v48, v50, v48
	v_mov_b32_e32 v84, v78
	v_mov_b32_e32 v85, v82
	v_mov_b32_e32 v82, v79
	v_add_f32_e32 v48, v77, v48
	v_pk_add_f32 v[78:79], v[84:85], v[82:83]
	v_add_f32_e32 v48, v76, v48
	v_add_f32_e32 v48, v79, v48
	v_add_f32_e32 v76, v78, v48
	ds_bpermute_b32 v77, v158, v76
	v_pk_mul_f32 v[50:51], v[70:71], v[80:81] op_sel_hi:[1,0]
	v_cvt_pk_bf16_f32 v48, v68, v69
	v_cvt_pk_bf16_f32 v49, v50, v51
	v_pk_mul_f32 v[50:51], v[90:91], v[80:81] op_sel_hi:[1,0]
	s_waitcnt lgkmcnt(0)
; __device__ __forceinline__ unsigned cvtpk(float lo, float hi) { f32x2_t v = {lo, hi}; bf16x2_t b = __builtin_convertvector(v, bf16x2_t); return __builtin_bit_cast(unsigned, b); }
;     __device__ __forceinline__ void operator()(const pg8::f32x4 (&acc)[2][2][4][2], const pg8::Unit& u, int wr, int wc, int fr, int fq) const {
;     ...
;                 for (int m = 0; m < 4; ++m) {
;                     const int row = rowq + ai * 128 + m * 16;
;                     const float rs = rsqrtf(rsq_[ai][m] * (1.f / DM) + EPS);
;                     const pg8::f32x4 a0 = acc[ai][0][m][0] * rs, a1 = acc[ai][0][m][1] * rs, b0 = acc[ai][1][m][0] * rs, b1 = acc[ai][1][m][1] * rs;
;                     float sq = (a0[0] * a0[0] + a0[1] * a0[1]) + (a0[2] * a0[2] + a0[3] * a0[3]) + (a1[0] * a1[0] + a1[1] * a1[1]) + (a1[2] * a1[2] + a1[3] * a1[3])
;                              + (b0[0] * b0[0] + b0[1] * b0[1]) + (b0[2] * b0[2] + b0[3] * b0[3]) + (b1[0] * b1[0] + b1[1] * b1[1]) + (b1[2] * b1[2] + b1[3] * b1[3]);
;                     sq += __shfl_xor(sq, 16); sq += __shfl_xor(sq, 32);
;                     const float rn = rsqrtf(sq * (1.f / 64.f) + EPS);
;                     u32x4 w0, w1;
;                     w0[0] = cvtpk(a0[0] * rn, a0[1] * rn); w0[1] = cvtpk(a0[2] * rn, a0[3] * rn); w0[2] = cvtpk(a1[0] * rn, a1[1] * rn); w0[3] = cvtpk(a1[2] * rn, a1[3] * rn);
;                     w1[0] = cvtpk(b0[0] * rn, b0[1] * rn); w1[1] = cvtpk(b0[2] * rn, b0[3] * rn); w1[2] = cvtpk(b1[0] * rn, b1[1] * rn); w1[3] = cvtpk(b1[2] * rn, b1[3] * rn);
;                     *(u32x4*)(qb_ + (size_t)row * 1024) = w0; *(u32x4*)(qb_ + (size_t)row * 1024 + 32) = w1;
	v_add_f32_e32 v70, v76, v77
	ds_bpermute_b32 v71, v144, v70
	v_pk_mul_f32 v[68:69], v[88:89], v[80:81] op_sel_hi:[1,0]
	v_cvt_pk_bf16_f32 v50, v50, v51
	v_cvt_pk_bf16_f32 v51, v68, v69
	v_lshlrev_b64 v[68:69], 11, v[128:129]
	s_waitcnt lgkmcnt(0)
	v_add_f32_e32 v70, v70, v71
	v_fmamk_f32 v70, v70, 0x3c800000, v176
	v_mul_f32_e32 v71, 0x4b800000, v70
	v_cmp_gt_f32_e32 vcc, s55, v70
	v_lshl_add_u64 v[68:69], v[132:133], 0, v[68:69]
	global_store_dwordx4 v[68:69], v[64:67], off
	global_store_dwordx4 v[68:69], v[48:51], off offset:64
	v_cndmask_b32_e32 v70, v70, v71, vcc
	v_rsq_f32_e32 v70, v70
	s_nop 0
	v_mul_f32_e32 v48, 0x45800000, v70
	v_cndmask_b32_e32 v64, v70, v48, vcc
	v_pk_mul_f32 v[48:49], v[60:61], v[64:65] op_sel_hi:[1,0]
	v_pk_mul_f32 v[50:51], v[62:63], v[64:65] op_sel_hi:[1,0]
	v_cvt_pk_bf16_f32 v48, v48, v49
	v_cvt_pk_bf16_f32 v49, v50, v51
	v_pk_mul_f32 v[50:51], v[56:57], v[64:65] op_sel_hi:[1,0]
	v_pk_mul_f32 v[52:53], v[52:53], v[64:65] op_sel_hi:[1,0]
	v_cvt_pk_bf16_f32 v50, v50, v51
	v_fmamk_f32 v51, v161, 0x3a000000, v176
	v_mul_f32_e32 v56, 0x4b800000, v51
	v_cmp_gt_f32_e32 vcc, s55, v51
	s_nop 1
	v_cndmask_b32_e32 v51, v51, v56, vcc
	v_rsq_f32_e32 v60, v51
	v_pk_mul_f32 v[56:57], v[58:59], v[64:65] op_sel_hi:[1,0]
	s_nop 0
	v_cvt_pk_bf16_f32 v51, v56, v57
	v_mul_f32_e32 v56, 0x45800000, v60
	v_cndmask_b32_e32 v56, v60, v56, vcc
	v_pk_mul_f32 v[44:45], v[44:45], v[56:57] op_sel_hi:[1,0]
	v_pk_mul_f32 v[46:47], v[46:47], v[56:57] op_sel_hi:[1,0]
	v_pk_mul_f32 v[40:41], v[40:41], v[56:57] op_sel_hi:[1,0]
	v_pk_mul_f32 v[42:43], v[42:43], v[56:57] op_sel_hi:[1,0]
	v_pk_mul_f32 v[36:37], v[36:37], v[56:57] op_sel_hi:[1,0]
	v_pk_mul_f32 v[38:39], v[38:39], v[56:57] op_sel_hi:[1,0]
	v_pk_mul_f32 v[58:59], v[32:33], v[56:57] op_sel_hi:[1,0]
	v_pk_mul_f32 v[56:57], v[34:35], v[56:57] op_sel_hi:[1,0]
	v_pk_mul_f32 v[32:33], v[46:47], v[46:47]
	v_pk_mul_f32 v[34:35], v[44:45], v[44:45]
	s_nop 0
	v_pk_mov_b32 v[60:61], v[34:35], v[32:33] op_sel:[1,0]
	v_mov_b32_e32 v35, v33
	v_pk_add_f32 v[32:33], v[60:61], v[34:35]
	v_pk_mul_f32 v[34:35], v[42:43], v[42:43]
	v_pk_mul_f32 v[60:61], v[40:41], v[40:41]
	v_mov_b32_e32 v62, v34
	v_mov_b32_e32 v63, v60
	v_mov_b32_e32 v60, v35
	v_pk_add_f32 v[34:35], v[62:63], v[60:61]
	v_pk_mul_f32 v[60:61], v[38:39], v[38:39]
	v_pk_mul_f32 v[62:63], v[36:37], v[36:37]
	v_add_f32_e32 v32, v32, v33
	v_mov_b32_e32 v66, v60
	v_mov_b32_e32 v67, v62
	v_mov_b32_e32 v62, v61
	v_add_f32_e32 v32, v35, v32
	v_pk_add_f32 v[60:61], v[66:67], v[62:63]
	v_pk_mul_f32 v[62:63], v[56:57], v[56:57]
	v_pk_mul_f32 v[66:67], v[58:59], v[58:59]
	v_add_f32_e32 v32, v34, v32
	v_mov_b32_e32 v68, v62
	v_mov_b32_e32 v69, v66
	v_mov_b32_e32 v66, v63
	v_add_f32_e32 v32, v61, v32
	v_pk_add_f32 v[62:63], v[68:69], v[66:67]
	v_add_f32_e32 v32, v60, v32
	v_add_f32_e32 v32, v63, v32
	v_add_f32_e32 v60, v62, v32
	ds_bpermute_b32 v61, v158, v60
	v_pk_mul_f32 v[34:35], v[54:55], v[64:65] op_sel_hi:[1,0]
	v_cvt_pk_bf16_f32 v32, v52, v53
	v_cvt_pk_bf16_f32 v33, v34, v35
	v_pk_mul_f32 v[34:35], v[74:75], v[64:65] op_sel_hi:[1,0]
	s_waitcnt lgkmcnt(0)
	v_add_f32_e32 v54, v60, v61
	ds_bpermute_b32 v55, v144, v54
	v_pk_mul_f32 v[52:53], v[72:73], v[64:65] op_sel_hi:[1,0]
	v_cvt_pk_bf16_f32 v34, v34, v35
	v_cvt_pk_bf16_f32 v35, v52, v53
	v_lshl_add_u64 v[52:53], v[96:97], 0, s[4:5]
	s_waitcnt lgkmcnt(0)
	v_add_f32_e32 v54, v54, v55
	v_fmamk_f32 v54, v54, 0x3c800000, v176
	v_mul_f32_e32 v55, 0x4b800000, v54
	v_cmp_gt_f32_e32 vcc, s55, v54
	s_nop 1
	v_cndmask_b32_e32 v54, v54, v55, vcc
	v_rsq_f32_e32 v60, v54
	v_add_co_u32_e64 v54, s[4:5], s57, v96
	s_nop 1
	v_addc_co_u32_e64 v55, s[4:5], 0, v97, s[4:5]
	global_store_dwordx4 v[54:55], v[48:51], off
	global_store_dwordx4 v[52:53], v[32:35], off offset:64
	s_nop 1
	v_mul_f32_e32 v32, 0x45800000, v60
	v_cndmask_b32_e32 v48, v60, v32, vcc
	v_pk_mul_f32 v[32:33], v[44:45], v[48:49] op_sel_hi:[1,0]
	v_pk_mul_f32 v[34:35], v[46:47], v[48:49] op_sel_hi:[1,0]
	v_cvt_pk_bf16_f32 v32, v32, v33
	v_cvt_pk_bf16_f32 v33, v34, v35
	v_pk_mul_f32 v[34:35], v[40:41], v[48:49] op_sel_hi:[1,0]
	v_pk_mul_f32 v[36:37], v[36:37], v[48:49] op_sel_hi:[1,0]
	v_cvt_pk_bf16_f32 v34, v34, v35
	v_fmamk_f32 v35, v160, 0x3a000000, v176
	v_mul_f32_e32 v40, 0x4b800000, v35
	v_cmp_gt_f32_e32 vcc, s55, v35
	s_nop 1
	v_cndmask_b32_e32 v35, v35, v40, vcc
	v_rsq_f32_e32 v44, v35
	v_pk_mul_f32 v[40:41], v[42:43], v[48:49] op_sel_hi:[1,0]
	s_nop 0
	v_cvt_pk_bf16_f32 v35, v40, v41
	v_mul_f32_e32 v40, 0x45800000, v44
	v_cndmask_b32_e32 v40, v44, v40, vcc
	v_pk_mul_f32 v[28:29], v[28:29], v[40:41] op_sel_hi:[1,0]
	v_pk_mul_f32 v[30:31], v[30:31], v[40:41] op_sel_hi:[1,0]
	v_pk_mul_f32 v[24:25], v[24:25], v[40:41] op_sel_hi:[1,0]
	v_pk_mul_f32 v[26:27], v[26:27], v[40:41] op_sel_hi:[1,0]
	v_pk_mul_f32 v[20:21], v[20:21], v[40:41] op_sel_hi:[1,0]
	v_pk_mul_f32 v[22:23], v[22:23], v[40:41] op_sel_hi:[1,0]
	v_pk_mul_f32 v[42:43], v[16:17], v[40:41] op_sel_hi:[1,0]
	v_pk_mul_f32 v[40:41], v[18:19], v[40:41] op_sel_hi:[1,0]
	v_pk_mul_f32 v[16:17], v[30:31], v[30:31]
	v_pk_mul_f32 v[18:19], v[28:29], v[28:29]
	s_nop 0
	v_pk_mov_b32 v[44:45], v[18:19], v[16:17] op_sel:[1,0]
	v_mov_b32_e32 v19, v17
	v_pk_add_f32 v[16:17], v[44:45], v[18:19]
	v_pk_mul_f32 v[18:19], v[26:27], v[26:27]
	v_pk_mul_f32 v[44:45], v[24:25], v[24:25]
	v_mov_b32_e32 v46, v18
	v_mov_b32_e32 v47, v44
	v_mov_b32_e32 v44, v19
	v_pk_add_f32 v[18:19], v[46:47], v[44:45]
	v_pk_mul_f32 v[44:45], v[22:23], v[22:23]
	v_pk_mul_f32 v[46:47], v[20:21], v[20:21]
	v_add_f32_e32 v16, v16, v17
	v_mov_b32_e32 v50, v44
	v_mov_b32_e32 v51, v46
	v_mov_b32_e32 v46, v45
	v_add_f32_e32 v16, v19, v16
	v_pk_add_f32 v[44:45], v[50:51], v[46:47]
	v_pk_mul_f32 v[46:47], v[40:41], v[40:41]
	v_pk_mul_f32 v[50:51], v[42:43], v[42:43]
	v_add_f32_e32 v16, v18, v16
	v_mov_b32_e32 v52, v46
	v_mov_b32_e32 v53, v50
	v_mov_b32_e32 v50, v47
	v_add_f32_e32 v16, v45, v16
	v_pk_add_f32 v[46:47], v[52:53], v[50:51]
	v_add_f32_e32 v16, v44, v16
	v_add_f32_e32 v16, v47, v16
	v_add_f32_e32 v44, v46, v16
	ds_bpermute_b32 v45, v158, v44
	v_pk_mul_f32 v[18:19], v[38:39], v[48:49] op_sel_hi:[1,0]
	v_cvt_pk_bf16_f32 v16, v36, v37
	v_cvt_pk_bf16_f32 v17, v18, v19
	v_pk_mul_f32 v[18:19], v[58:59], v[48:49] op_sel_hi:[1,0]
	s_waitcnt lgkmcnt(0)
; __device__ __forceinline__ unsigned cvtpk(float lo, float hi) { f32x2_t v = {lo, hi}; bf16x2_t b = __builtin_convertvector(v, bf16x2_t); return __builtin_bit_cast(unsigned, b); }
;     __device__ __forceinline__ void operator()(const pg8::f32x4 (&acc)[2][2][4][2], const pg8::Unit& u, int wr, int wc, int fr, int fq) const {
;     ...
;                 for (int m = 0; m < 4; ++m) {
;                     const int row = rowq + ai * 128 + m * 16;
;                     const float rs = rsqrtf(rsq_[ai][m] * (1.f / DM) + EPS);
;                     const pg8::f32x4 a0 = acc[ai][0][m][0] * rs, a1 = acc[ai][0][m][1] * rs, b0 = acc[ai][1][m][0] * rs, b1 = acc[ai][1][m][1] * rs;
;                     float sq = (a0[0] * a0[0] + a0[1] * a0[1]) + (a0[2] * a0[2] + a0[3] * a0[3]) + (a1[0] * a1[0] + a1[1] * a1[1]) + (a1[2] * a1[2] + a1[3] * a1[3])
;                              + (b0[0] * b0[0] + b0[1] * b0[1]) + (b0[2] * b0[2] + b0[3] * b0[3]) + (b1[0] * b1[0] + b1[1] * b1[1]) + (b1[2] * b1[2] + b1[3] * b1[3]);
;                     sq += __shfl_xor(sq, 16); sq += __shfl_xor(sq, 32);
;                     const float rn = rsqrtf(sq * (1.f / 64.f) + EPS);
;                     u32x4 w0, w1;
;                     w0[0] = cvtpk(a0[0] * rn, a0[1] * rn); w0[1] = cvtpk(a0[2] * rn, a0[3] * rn); w0[2] = cvtpk(a1[0] * rn, a1[1] * rn); w0[3] = cvtpk(a1[2] * rn, a1[3] * rn);
;                     w1[0] = cvtpk(b0[0] * rn, b0[1] * rn); w1[1] = cvtpk(b0[2] * rn, b0[3] * rn); w1[2] = cvtpk(b1[0] * rn, b1[1] * rn); w1[3] = cvtpk(b1[2] * rn, b1[3] * rn);
;                     *(u32x4*)(qb_ + (size_t)row * 1024) = w0; *(u32x4*)(qb_ + (size_t)row * 1024 + 32) = w1;
;                 }
;             return;
	v_add_f32_e32 v38, v44, v45
	ds_bpermute_b32 v39, v144, v38
	v_pk_mul_f32 v[36:37], v[56:57], v[48:49] op_sel_hi:[1,0]
	v_cvt_pk_bf16_f32 v18, v18, v19
	v_cvt_pk_bf16_f32 v19, v36, v37
	v_lshl_add_u64 v[36:37], v[96:97], 0, s[20:21]
	s_waitcnt lgkmcnt(0)
	v_add_f32_e32 v38, v38, v39
	v_fmamk_f32 v38, v38, 0x3c800000, v176
	v_mul_f32_e32 v39, 0x4b800000, v38
	v_cmp_gt_f32_e32 vcc, s55, v38
	s_nop 1
	v_cndmask_b32_e32 v38, v38, v39, vcc
	v_rsq_f32_e32 v44, v38
	v_add_co_u32_e64 v38, s[4:5], s58, v96
	s_nop 1
	v_addc_co_u32_e64 v39, s[4:5], 0, v97, s[4:5]
	global_store_dwordx4 v[38:39], v[32:35], off
	global_store_dwordx4 v[36:37], v[16:19], off offset:64
	s_nop 1
	v_mul_f32_e32 v16, 0x45800000, v44
	v_cndmask_b32_e32 v32, v44, v16, vcc
	v_pk_mul_f32 v[16:17], v[28:29], v[32:33] op_sel_hi:[1,0]
	v_pk_mul_f32 v[18:19], v[30:31], v[32:33] op_sel_hi:[1,0]
	v_cvt_pk_bf16_f32 v16, v16, v17
	v_cvt_pk_bf16_f32 v17, v18, v19
	v_pk_mul_f32 v[18:19], v[24:25], v[32:33] op_sel_hi:[1,0]
	v_pk_mul_f32 v[20:21], v[20:21], v[32:33] op_sel_hi:[1,0]
	v_cvt_pk_bf16_f32 v18, v18, v19
	v_fmamk_f32 v19, v159, 0x3a000000, v176
	v_mul_f32_e32 v24, 0x4b800000, v19
	v_cmp_gt_f32_e32 vcc, s55, v19
	s_nop 1
	v_cndmask_b32_e32 v19, v19, v24, vcc
	v_rsq_f32_e32 v28, v19
	v_pk_mul_f32 v[24:25], v[26:27], v[32:33] op_sel_hi:[1,0]
	s_nop 0
	v_cvt_pk_bf16_f32 v19, v24, v25
	v_mul_f32_e32 v24, 0x45800000, v28
	v_cndmask_b32_e32 v24, v28, v24, vcc
	v_pk_mul_f32 v[12:13], v[12:13], v[24:25] op_sel_hi:[1,0]
	v_pk_mul_f32 v[14:15], v[14:15], v[24:25] op_sel_hi:[1,0]
	v_pk_mul_f32 v[8:9], v[8:9], v[24:25] op_sel_hi:[1,0]
	v_pk_mul_f32 v[10:11], v[10:11], v[24:25] op_sel_hi:[1,0]
	v_pk_mul_f32 v[4:5], v[4:5], v[24:25] op_sel_hi:[1,0]
	v_pk_mul_f32 v[6:7], v[6:7], v[24:25] op_sel_hi:[1,0]
	v_pk_mul_f32 v[26:27], v[0:1], v[24:25] op_sel_hi:[1,0]
	v_pk_mul_f32 v[24:25], v[2:3], v[24:25] op_sel_hi:[1,0]
	v_pk_mul_f32 v[0:1], v[14:15], v[14:15]
	v_pk_mul_f32 v[2:3], v[12:13], v[12:13]
	s_nop 0
	v_pk_mov_b32 v[28:29], v[2:3], v[0:1] op_sel:[1,0]
	v_mov_b32_e32 v3, v1
	v_pk_add_f32 v[0:1], v[28:29], v[2:3]
	v_pk_mul_f32 v[2:3], v[10:11], v[10:11]
	v_pk_mul_f32 v[28:29], v[8:9], v[8:9]
	v_mov_b32_e32 v30, v2
	v_mov_b32_e32 v31, v28
	v_mov_b32_e32 v28, v3
	v_pk_add_f32 v[2:3], v[30:31], v[28:29]
	v_pk_mul_f32 v[28:29], v[6:7], v[6:7]
	v_pk_mul_f32 v[30:31], v[4:5], v[4:5]
	v_add_f32_e32 v0, v0, v1
	v_mov_b32_e32 v34, v28
	v_mov_b32_e32 v35, v30
	v_mov_b32_e32 v30, v29
	v_add_f32_e32 v0, v3, v0
	v_pk_add_f32 v[28:29], v[34:35], v[30:31]
	v_pk_mul_f32 v[30:31], v[24:25], v[24:25]
	v_pk_mul_f32 v[34:35], v[26:27], v[26:27]
	v_add_f32_e32 v0, v2, v0
	v_mov_b32_e32 v36, v30
	v_mov_b32_e32 v37, v34
	v_mov_b32_e32 v34, v31
	v_add_f32_e32 v0, v29, v0
	v_pk_add_f32 v[30:31], v[36:37], v[34:35]
	v_add_f32_e32 v0, v28, v0
	v_add_f32_e32 v0, v31, v0
	v_add_f32_e32 v28, v30, v0
	ds_bpermute_b32 v29, v158, v28
	v_pk_mul_f32 v[2:3], v[22:23], v[32:33] op_sel_hi:[1,0]
	v_cvt_pk_bf16_f32 v0, v20, v21
	v_cvt_pk_bf16_f32 v1, v2, v3
	v_pk_mul_f32 v[2:3], v[42:43], v[32:33] op_sel_hi:[1,0]
	s_waitcnt lgkmcnt(0)
	v_add_f32_e32 v22, v28, v29
	ds_bpermute_b32 v23, v144, v22
	v_pk_mul_f32 v[20:21], v[40:41], v[32:33] op_sel_hi:[1,0]
	v_cvt_pk_bf16_f32 v2, v2, v3
	v_cvt_pk_bf16_f32 v3, v20, v21
	v_lshl_add_u64 v[20:21], v[96:97], 0, s[22:23]
	s_waitcnt lgkmcnt(0)
	v_add_f32_e32 v22, v22, v23
	v_fmamk_f32 v22, v22, 0x3c800000, v176
	v_mul_f32_e32 v23, 0x4b800000, v22
	v_cmp_gt_f32_e32 vcc, s55, v22
	s_nop 1
	v_cndmask_b32_e32 v22, v22, v23, vcc
	v_rsq_f32_e32 v28, v22
	v_add_co_u32_e64 v22, s[4:5], s59, v96
	s_nop 1
	v_addc_co_u32_e64 v23, s[4:5], 0, v97, s[4:5]
	global_store_dwordx4 v[22:23], v[16:19], off
	global_store_dwordx4 v[20:21], v[0:3], off offset:64
	s_nop 1
	v_mul_f32_e32 v0, 0x45800000, v28
	v_cndmask_b32_e32 v16, v28, v0, vcc
	v_pk_mul_f32 v[0:1], v[12:13], v[16:17] op_sel_hi:[1,0]
	v_pk_mul_f32 v[2:3], v[14:15], v[16:17] op_sel_hi:[1,0]
	v_cvt_pk_bf16_f32 v0, v0, v1
	v_cvt_pk_bf16_f32 v1, v2, v3
	v_pk_mul_f32 v[2:3], v[8:9], v[16:17] op_sel_hi:[1,0]
	v_pk_mul_f32 v[8:9], v[10:11], v[16:17] op_sel_hi:[1,0]
	v_pk_mul_f32 v[4:5], v[4:5], v[16:17] op_sel_hi:[1,0]
	v_pk_mul_f32 v[6:7], v[6:7], v[16:17] op_sel_hi:[1,0]
	v_add_co_u32_e32 v10, vcc, 0x58000, v96
	v_cvt_pk_bf16_f32 v2, v2, v3
	v_cvt_pk_bf16_f32 v3, v8, v9
	v_cvt_pk_bf16_f32 v4, v4, v5
	v_cvt_pk_bf16_f32 v5, v6, v7
	v_pk_mul_f32 v[6:7], v[26:27], v[16:17] op_sel_hi:[1,0]
	v_pk_mul_f32 v[8:9], v[24:25], v[16:17] op_sel_hi:[1,0]
	v_addc_co_u32_e32 v11, vcc, 0, v97, vcc
	v_cvt_pk_bf16_f32 v6, v6, v7
	v_cvt_pk_bf16_f32 v7, v8, v9
	v_lshl_add_u64 v[8:9], v[96:97], 0, s[24:25]
	global_store_dwordx4 v[10:11], v[0:3], off
	global_store_dwordx4 v[8:9], v[4:7], off offset:64
	s_andn2_b64 vcc, exec, s[2:3]
	s_mov_b64 s[2:3], -1
	s_cbranch_vccnz .LBB0_366

; __device__ __forceinline__ unsigned xb_add(unsigned* p, unsigned v) { return __hip_atomic_fetch_add(p, v, __ATOMIC_RELAXED, __HIP_MEMORY_SCOPE_AGENT); }
; #define SEAM(k) do { if (IN(k) && IN((k) + 1)) xcd_barrier(xbar); } while (0)
; __device__ __forceinline__ void xcd_barrier(const XcdBarrier& b) {
;     asm volatile("s_waitcnt vmcnt(0)" ::: "memory");
;     __syncthreads();
;     if (threadIdx.x == 0) {
;         unsigned* bar = b.bar;
;         __builtin_amdgcn_s_waitcnt(0);
;         unsigned nloc = b.st[0], nx = b.st[1];
;         if (nloc == 0u) { xcd_barrier_complete(bar, b.x, nloc, nx); b.st[0] = nloc; b.st[1] = nx; }
;         const unsigned old = xb_add(&bar[XB_XSUB(b.x)], 1u);
;         const unsigned gen = old / nloc;
;         if (old + 1u == (gen + 1u) * nloc) {
;             __builtin_amdgcn_fence(__ATOMIC_RELEASE, "agent");
;             asm volatile("s_waitcnt vmcnt(0)" ::: "memory");
;             const unsigned og = xb_add(&bar[XB_TOP], 1u);
;             const unsigned tg = og / nx;
;             if (og + 1u == (tg + 1u) * nx) xb_add(&bar[XB_TOPGEN], 1u);
; __global__ void __launch_bounds__(512, 2) fwd_megakernel(Args a) {
;     ...
;     SEAM(7);
.LBB0_1130:
	s_cmp_gt_i32 s67, 8
	s_cselect_b64 s[0:1], -1, 0
	s_and_b64 s[2:3], s[8:9], s[0:1]
	s_andn2_b64 vcc, exec, s[2:3]
	s_cbranch_vccnz .LBB0_1180
	s_waitcnt vmcnt(0)
	v_cmp_eq_u32_e32 vcc, 0, v220
	s_waitcnt vmcnt(0) lgkmcnt(0)
	s_barrier
	s_and_saveexec_b64 s[2:3], vcc
	s_cbranch_execz .LBB0_1179
	buffer_wbl2 sc1
	s_waitcnt vmcnt(0) lgkmcnt(0)
	s_and_b32 s100, s77, 7
	s_lshl_b32 s101, s100, 6
	s_add_u32 s98, s64, s101
	s_addc_u32 s99, s65, 0
	s_add_u32 s98, s98, 0x83800
	s_addc_u32 s99, s99, 0
	s_sub_i32 s100, s82, s100
	s_add_i32 s100, s100, 7
	s_lshr_b32 s100, s100, 3
	s_add_i32 s100, s100, -1
	v_mov_b32_e32 v0, 0
	v_mov_b32_e32 v1, 1
	global_atomic_add v2, v0, v1, s[98:99] sc0
	s_waitcnt vmcnt(0)
	v_cmp_eq_u32_e32 vcc, s100, v2
	s_cbranch_vccnz .Lgb_release_7

; __device__ __forceinline__ unsigned xb_add(unsigned* p, unsigned v) { return __hip_atomic_fetch_add(p, v, __ATOMIC_RELAXED, __HIP_MEMORY_SCOPE_AGENT); }
; #define SEAM(k) do { if (IN(k) && IN((k) + 1)) xcd_barrier(xbar); } while (0)
; __device__ __forceinline__ void xcd_barrier(const XcdBarrier& b) {
;     asm volatile("s_waitcnt vmcnt(0)" ::: "memory");
;     __syncthreads();
;     if (threadIdx.x == 0) {
;         unsigned* bar = b.bar;
;         __builtin_amdgcn_s_waitcnt(0);
;         unsigned nloc = b.st[0], nx = b.st[1];
;         if (nloc == 0u) { xcd_barrier_complete(bar, b.x, nloc, nx); b.st[0] = nloc; b.st[1] = nx; }
;         const unsigned old = xb_add(&bar[XB_XSUB(b.x)], 1u);
;         const unsigned gen = old / nloc;
;         if (old + 1u == (gen + 1u) * nloc) {
;             __builtin_amdgcn_fence(__ATOMIC_RELEASE, "agent");
;             asm volatile("s_waitcnt vmcnt(0)" ::: "memory");
;             const unsigned og = xb_add(&bar[XB_TOP], 1u);
;             const unsigned tg = og / nx;
;             if (og + 1u == (tg + 1u) * nx) xb_add(&bar[XB_TOPGEN], 1u);
; __global__ void __launch_bounds__(512, 2) fwd_megakernel(Args a) {
;     ...
;     SEAM(8);
.LBB0_1227:
	s_cmp_gt_i32 s67, 9
	s_cselect_b64 s[0:1], -1, 0
	s_and_b64 s[2:3], s[8:9], s[0:1]
	s_andn2_b64 vcc, exec, s[2:3]
	s_cbranch_vccnz .LBB0_1277
	s_waitcnt vmcnt(0)
	v_cmp_eq_u32_e32 vcc, 0, v220
	s_waitcnt vmcnt(0) lgkmcnt(0)
	s_barrier
	s_and_saveexec_b64 s[2:3], vcc
	s_cbranch_execz .LBB0_1276
	buffer_wbl2 sc1
	s_waitcnt vmcnt(0) lgkmcnt(0)
	s_and_b32 s100, s77, 7
	s_lshl_b32 s101, s100, 6
	s_add_u32 s98, s64, s101
	s_addc_u32 s99, s65, 0
	s_add_u32 s98, s98, 0x83a00
	s_addc_u32 s99, s99, 0
	s_sub_i32 s100, s82, s100
	s_add_i32 s100, s100, 7
	s_lshr_b32 s100, s100, 3
	s_add_i32 s100, s100, -1
	v_mov_b32_e32 v0, 0
	v_mov_b32_e32 v1, 1
	global_atomic_add v2, v0, v1, s[98:99] sc0
	s_waitcnt vmcnt(0)
	v_cmp_eq_u32_e32 vcc, s100, v2
	s_cbranch_vccnz .Lgb_release_8

; __global__ void __launch_bounds__(512, 2) fwd_megakernel(Args a) {
	.amdhsa_kernel _Z14fwd_megakernel4Args
		.amdhsa_group_segment_fixed_size 0
		.amdhsa_private_segment_fixed_size 0
		.amdhsa_kernarg_size 512
		.amdhsa_user_sgpr_count 2
		.amdhsa_user_sgpr_dispatch_ptr 0
		.amdhsa_user_sgpr_queue_ptr 0
		.amdhsa_user_sgpr_kernarg_segment_ptr 1
		.amdhsa_user_sgpr_dispatch_id 0
		.amdhsa_user_sgpr_kernarg_preload_length 0
		.amdhsa_user_sgpr_kernarg_preload_offset 0
		.amdhsa_user_sgpr_private_segment_size 0
		.amdhsa_uses_dynamic_stack 0
		.amdhsa_enable_private_segment 0
		.amdhsa_system_sgpr_workgroup_id_x 1
		.amdhsa_system_sgpr_workgroup_id_y 0
		.amdhsa_system_sgpr_workgroup_id_z 0
		.amdhsa_system_sgpr_workgroup_info 0
		.amdhsa_system_vgpr_workitem_id 2
		.amdhsa_next_free_vgpr 251
		.amdhsa_next_free_sgpr 102
		.amdhsa_accum_offset 252
		.amdhsa_reserve_vcc 1
		.amdhsa_float_round_mode_32 0
		.amdhsa_float_round_mode_16_64 0
		.amdhsa_float_denorm_mode_32 3
		.amdhsa_float_denorm_mode_16_64 3
		.amdhsa_dx10_clamp 1
		.amdhsa_ieee_mode 1
		.amdhsa_fp16_overflow 0
		.amdhsa_tg_split 0
		.amdhsa_exception_fp_ieee_invalid_op 0
		.amdhsa_exception_fp_denorm_src 0
		.amdhsa_exception_fp_ieee_div_zero 0
		.amdhsa_exception_fp_ieee_overflow 0
		.amdhsa_exception_fp_ieee_underflow 0
		.amdhsa_exception_fp_ieee_inexact 0
		.amdhsa_exception_int_div_zero 0
	.end_amdhsa_kernel

; __global__ void __launch_bounds__(512, 2) fwd_megakernel(Args a) {
amdhsa.kernels:
  - .agpr_count:     0
    .args:
      - .offset:         0
        .size:           256
        .value_kind:     by_value
      - .offset:         256
        .size:           4
        .value_kind:     hidden_block_count_x
      - .offset:         260
        .size:           4
        .value_kind:     hidden_block_count_y
      - .offset:         264
        .size:           4
        .value_kind:     hidden_block_count_z
      - .offset:         268
        .size:           2
        .value_kind:     hidden_group_size_x
      - .offset:         270
        .size:           2
        .value_kind:     hidden_group_size_y
      - .offset:         272
        .size:           2
        .value_kind:     hidden_group_size_z
      - .offset:         274
        .size:           2
        .value_kind:     hidden_remainder_x
      - .offset:         276
        .size:           2
        .value_kind:     hidden_remainder_y
      - .offset:         278
        .size:           2
        .value_kind:     hidden_remainder_z
      - .offset:         296
        .size:           8
        .value_kind:     hidden_global_offset_x
      - .offset:         304
        .size:           8
        .value_kind:     hidden_global_offset_y
      - .offset:         312
        .size:           8
        .value_kind:     hidden_global_offset_z
      - .offset:         320
        .size:           2
        .value_kind:     hidden_grid_dims
      - .offset:         344
        .size:           8
        .value_kind:     hidden_multigrid_sync_arg
      - .offset:         376
        .size:           4
        .value_kind:     hidden_dynamic_lds_size
    .group_segment_fixed_size: 0
    .kernarg_segment_align: 8
    .kernarg_segment_size: 512
    .language:       OpenCL C
    .language_version:
      - 2
      - 0
    .max_flat_workgroup_size: 512
    .name:           _Z14fwd_megakernel4Args
    .private_segment_fixed_size: 0
    .sgpr_count:     108
    .sgpr_spill_count: 38
    .symbol:         _Z14fwd_megakernel4Args.kd
    .uniform_work_group_size: 1
    .uses_dynamic_stack: false
    .vgpr_count:     251
    .vgpr_spill_count: 0
    .wavefront_size: 64
